# speedup vs baseline: 1.0060x; 1.0060x over previous
; __device__ __forceinline__ unsigned pk2(float lo, float hi) { f32x2_t v = {lo, hi}; bf16x2_t b = __builtin_convertvector(v, bf16x2_t); return __builtin_bit_cast(unsigned, b); }
; __device__ __forceinline__ float bf_lo(unsigned w) { return __uint_as_float(w << 16); }
; __device__ __forceinline__ float bf_hi(unsigned w) { return __uint_as_float(w & 0xffff0000u); }
; __device__ __forceinline__ float xsum32(float v) { auto rr = __builtin_amdgcn_permlane32_swap(__float_as_uint(v), __float_as_uint(v), false, false); return __uint_as_float(rr[0]) + __uint_as_float(rr[1]); }
; __device__ __forceinline__ float xsum16(float v) { return v + __int_as_float(__builtin_amdgcn_ds_swizzle(__float_as_int(v), 0x401F)); }
;     __device__ __forceinline__ void operator()(const f32x4 (&acc)[2][2][4][2], const Unit& u, int wr, int wc, int fr, int fq) const {
;     ...
;             for (int m = 0; m < 4; ++m) { const size_t off = (size_t)(row0 + ai * HALF + m * 16) * DM + col0; float sq = 0.f;
; #pragma unroll
;                 for (int bj = 0; bj < 2; ++bj) { f32x4 o[2];
;                     if (bbase) { const u32x4 w = *(const u32x4*)(bbase + off + bj * HALF);
;                         o[0] = (f32x4){bf_lo(w.x), bf_hi(w.x), bf_lo(w.y), bf_hi(w.y)} + acc[ai][bj][m][0]; o[1] = (f32x4){bf_lo(w.z), bf_hi(w.z), bf_lo(w.w), bf_hi(w.w)} + acc[ai][bj][m][1]; }
;                     else { o[0] = *(const f32x4*)(base + off + bj * HALF) + acc[ai][bj][m][0]; o[1] = *(const f32x4*)(base + off + bj * HALF + 4) + acc[ai][bj][m][1]; }
; #pragma unroll
;                     for (int n = 0; n < 2; ++n) { if (out) *(f32x4*)(out + off + bj * HALF + 4 * n) = o[n];
;                         sq += (o[n][0] * o[n][0] + o[n][1] * o[n][1]) + (o[n][2] * o[n][2] + o[n][3] * o[n][3]); }
;                     if (xb) { u32x4 w; w.x = pk2(o[0][0], o[0][1]); w.y = pk2(o[0][2], o[0][3]); w.z = pk2(o[1][0], o[1][1]); w.w = pk2(o[1][2], o[1][3]); *(u32x4*)(xb + off + bj * HALF) = w; if (xb2) *(u32x4*)(xb2 + off + bj * HALF) = w; } }
;                 if (ss) { sq = xsum16(sq); sq = xsum32(sq); if (fq == 0) unsafeAtomicAdd(ss + row0 + ai * HALF + m * 16, sq); } }
.LBB0_536:
	v_lshl_add_u32 v156, s28, 8, v131
	v_ashrrev_i32_e32 v157, 31, v156
	v_lshl_or_b32 v154, s26, 8, v158
	v_lshlrev_b64 v[152:153], 11, v[156:157]
	v_ashrrev_i32_e32 v155, 31, v154
	v_lshl_add_u64 v[152:153], s[68:69], 0, v[152:153]
	v_lshl_add_u64 v[152:153], v[154:155], 1, v[152:153]
	v_mov_b32_e32 v252, v152
	v_mov_b32_e32 v253, v153
	global_load_dwordx4 v[178:181], v[252:253], off
	global_load_dwordx4 v[182:185], v[252:253], off offset:256
	s_mov_b32 s98, 0x8000
	s_mov_b32 s99, 0
	v_lshl_add_u64 v[254:255], v[252:253], 0, s[98:99]
	global_load_dwordx4 v[186:189], v[254:255], off
	global_load_dwordx4 v[194:197], v[254:255], off offset:256
	s_mov_b32 s98, 0x10000
	s_mov_b32 s99, 0
	v_lshl_add_u64 v[254:255], v[252:253], 0, s[98:99]
	global_load_dwordx4 v[198:201], v[254:255], off
	global_load_dwordx4 v[202:205], v[254:255], off offset:256
	s_mov_b32 s98, 0x18000
	s_mov_b32 s99, 0
	v_lshl_add_u64 v[254:255], v[252:253], 0, s[98:99]
	global_load_dwordx4 v[208:211], v[254:255], off
	global_load_dwordx4 v[212:215], v[254:255], off offset:256
	s_waitcnt vmcnt(0)
	s_nop 1
	v_mov_b32_e32 v162, v178
	v_mov_b32_e32 v163, v179
	v_mov_b32_e32 v164, v180
	v_mov_b32_e32 v165, v181
	s_nop 1
	v_mov_b32_e32 v166, v182
	v_mov_b32_e32 v167, v183
	v_mov_b32_e32 v168, v184
	v_mov_b32_e32 v169, v185
	s_andn2_b64 vcc, exec, s[16:17]
	v_lshlrev_b32_e32 v170, 16, v162
	v_and_b32_e32 v171, 0xffff0000, v162
	v_lshlrev_b32_e32 v162, 16, v163
	v_and_b32_e32 v163, 0xffff0000, v163
	v_lshlrev_b32_e32 v172, 16, v164
	v_and_b32_e32 v173, 0xffff0000, v164
	v_lshlrev_b32_e32 v164, 16, v165
	v_and_b32_e32 v165, 0xffff0000, v165
	v_lshlrev_b32_e32 v174, 16, v166
	v_and_b32_e32 v175, 0xffff0000, v166
	v_lshlrev_b32_e32 v166, 16, v167
	v_and_b32_e32 v167, 0xffff0000, v167
	v_lshlrev_b32_e32 v176, 16, v168
	v_and_b32_e32 v177, 0xffff0000, v168
	v_lshlrev_b32_e32 v168, 16, v169
	v_and_b32_e32 v169, 0xffff0000, v169
	v_pk_add_f32 v[126:127], v[126:127], v[162:163]
	v_pk_add_f32 v[124:125], v[124:125], v[170:171]
	v_pk_add_f32 v[122:123], v[122:123], v[164:165]
	v_pk_add_f32 v[120:121], v[120:121], v[172:173]
	v_pk_add_f32 v[118:119], v[118:119], v[166:167]
	v_pk_add_f32 v[116:117], v[116:117], v[174:175]
	v_pk_add_f32 v[114:115], v[114:115], v[168:169]
	v_pk_add_f32 v[112:113], v[112:113], v[176:177]
	v_cvt_pk_bf16_f32 v162, v124, v125
	v_cvt_pk_bf16_f32 v163, v126, v127
	v_cvt_pk_bf16_f32 v164, v120, v121
	v_cvt_pk_bf16_f32 v165, v122, v123
	v_cvt_pk_bf16_f32 v166, v116, v117
	v_cvt_pk_bf16_f32 v167, v118, v119
	v_cvt_pk_bf16_f32 v168, v112, v113
	v_cvt_pk_bf16_f32 v169, v114, v115
	global_store_dwordx4 v[152:153], v[162:165], off
	global_store_dwordx4 v[152:153], v[166:169], off offset:256
	s_cbranch_vccnz .LBB0_540
	v_mul_f32_e32 v113, v113, v113
	v_fmac_f32_e32 v113, v112, v112
	v_mul_f32_e32 v112, v115, v115
	v_fmac_f32_e32 v112, v114, v114
	v_add_f32_e32 v112, v113, v112
	v_mul_f32_e32 v113, v125, v125
	v_mul_f32_e32 v114, v127, v127
	v_fmac_f32_e32 v113, v124, v124
	v_fmac_f32_e32 v114, v126, v126
	v_add_f32_e32 v113, v113, v114
	v_mul_f32_e32 v114, v121, v121
	v_mul_f32_e32 v115, v123, v123
	v_fmac_f32_e32 v114, v120, v120
	v_fmac_f32_e32 v115, v122, v122
	v_add_f32_e32 v114, v114, v115
	v_add_f32_e32 v113, v113, v114
	v_mul_f32_e32 v114, v117, v117
	v_mul_f32_e32 v115, v119, v119
	v_fmac_f32_e32 v114, v116, v116
	v_fmac_f32_e32 v115, v118, v118
	v_add_f32_e32 v114, v114, v115
	v_add_f32_e32 v113, v113, v114
	v_add_f32_e32 v112, v112, v113
	ds_swizzle_b32 v113, v112 offset:swizzle(SWAP,16)
	s_waitcnt lgkmcnt(0)
	v_add_f32_e32 v112, v112, v113
	v_mov_b32_e32 v113, v112
	s_nop 1
	v_permlane32_swap_b32_e32 v112, v113
	s_and_saveexec_b64 s[4:5], s[6:7]
	s_cbranch_execz .LBB0_539
	v_lshl_add_u64 v[114:115], v[156:157], 2, s[12:13]
	v_add_f32_e32 v112, v112, v113
	global_atomic_add_f32 v[114:115], v112, off

; __device__ __forceinline__ unsigned pk2(float lo, float hi) { f32x2_t v = {lo, hi}; bf16x2_t b = __builtin_convertvector(v, bf16x2_t); return __builtin_bit_cast(unsigned, b); }
; __device__ __forceinline__ float bf_lo(unsigned w) { return __uint_as_float(w << 16); }
; __device__ __forceinline__ float bf_hi(unsigned w) { return __uint_as_float(w & 0xffff0000u); }
; __device__ __forceinline__ float xsum32(float v) { auto rr = __builtin_amdgcn_permlane32_swap(__float_as_uint(v), __float_as_uint(v), false, false); return __uint_as_float(rr[0]) + __uint_as_float(rr[1]); }
; __device__ __forceinline__ float xsum16(float v) { return v + __int_as_float(__builtin_amdgcn_ds_swizzle(__float_as_int(v), 0x401F)); }
;     __device__ __forceinline__ void operator()(const f32x4 (&acc)[2][2][4][2], const Unit& u, int wr, int wc, int fr, int fq) const {
;     ...
;             for (int m = 0; m < 4; ++m) { const size_t off = (size_t)(row0 + ai * HALF + m * 16) * DM + col0; float sq = 0.f;
; #pragma unroll
;                 for (int bj = 0; bj < 2; ++bj) { f32x4 o[2];
;                     if (bbase) { const u32x4 w = *(const u32x4*)(bbase + off + bj * HALF);
;                         o[0] = (f32x4){bf_lo(w.x), bf_hi(w.x), bf_lo(w.y), bf_hi(w.y)} + acc[ai][bj][m][0]; o[1] = (f32x4){bf_lo(w.z), bf_hi(w.z), bf_lo(w.w), bf_hi(w.w)} + acc[ai][bj][m][1]; }
;                     else { o[0] = *(const f32x4*)(base + off + bj * HALF) + acc[ai][bj][m][0]; o[1] = *(const f32x4*)(base + off + bj * HALF + 4) + acc[ai][bj][m][1]; }
; #pragma unroll
;                     for (int n = 0; n < 2; ++n) { if (out) *(f32x4*)(out + off + bj * HALF + 4 * n) = o[n];
;                         sq += (o[n][0] * o[n][0] + o[n][1] * o[n][1]) + (o[n][2] * o[n][2] + o[n][3] * o[n][3]); }
;                     if (xb) { u32x4 w; w.x = pk2(o[0][0], o[0][1]); w.y = pk2(o[0][2], o[0][3]); w.z = pk2(o[1][0], o[1][1]); w.w = pk2(o[1][2], o[1][3]); *(u32x4*)(xb + off + bj * HALF) = w; if (xb2) *(u32x4*)(xb2 + off + bj * HALF) = w; } }
;                 if (ss) { sq = xsum16(sq); sq = xsum32(sq); if (fq == 0) unsafeAtomicAdd(ss + row0 + ai * HALF + m * 16, sq); } }
.LBB0_540:
	v_or_b32_e32 v112, 16, v156
	v_ashrrev_i32_e32 v113, 31, v112
	v_lshlrev_b64 v[112:113], 11, v[112:113]
	v_lshl_add_u64 v[112:113], s[68:69], 0, v[112:113]
	v_lshl_add_u64 v[120:121], v[154:155], 1, v[112:113]
	s_nop 1
	v_mov_b32_e32 v112, v186
	v_mov_b32_e32 v113, v187
	v_mov_b32_e32 v114, v188
	v_mov_b32_e32 v115, v189
	s_nop 1
	v_mov_b32_e32 v116, v194
	v_mov_b32_e32 v117, v195
	v_mov_b32_e32 v118, v196
	v_mov_b32_e32 v119, v197
	s_mov_b32 s98, 0x40000
	s_mov_b32 s99, 0
	v_lshl_add_u64 v[254:255], v[252:253], 0, s[98:99]
	global_load_dwordx4 v[216:219], v[254:255], off
	global_load_dwordx4 v[220:223], v[254:255], off offset:256
	s_mov_b32 s98, 0x48000
	s_mov_b32 s99, 0
	v_lshl_add_u64 v[254:255], v[252:253], 0, s[98:99]
	global_load_dwordx4 v[224:227], v[254:255], off
	global_load_dwordx4 v[248:251], v[254:255], off offset:256
	s_mov_b32 s98, 0x50000
	s_mov_b32 s99, 0
	v_lshl_add_u64 v[254:255], v[252:253], 0, s[98:99]
	global_load_dwordx4 v[178:181], v[254:255], off
	global_load_dwordx4 v[182:185], v[254:255], off offset:256
	s_mov_b32 s98, 0x58000
	s_mov_b32 s99, 0
	v_lshl_add_u64 v[254:255], v[252:253], 0, s[98:99]
	global_load_dwordx4 v[186:189], v[254:255], off
	global_load_dwordx4 v[194:197], v[254:255], off offset:256
	v_lshlrev_b32_e32 v122, 16, v112
	v_and_b32_e32 v123, 0xffff0000, v112
	v_lshlrev_b32_e32 v112, 16, v113
	v_and_b32_e32 v113, 0xffff0000, v113
	v_lshlrev_b32_e32 v124, 16, v114
	v_and_b32_e32 v125, 0xffff0000, v114
	v_lshlrev_b32_e32 v114, 16, v115
	v_and_b32_e32 v115, 0xffff0000, v115
	v_lshlrev_b32_e32 v126, 16, v116
	v_and_b32_e32 v127, 0xffff0000, v116
	v_lshlrev_b32_e32 v116, 16, v117
	v_and_b32_e32 v117, 0xffff0000, v117
	v_lshlrev_b32_e32 v162, 16, v118
	v_and_b32_e32 v163, 0xffff0000, v118
	v_lshlrev_b32_e32 v118, 16, v119
	v_and_b32_e32 v119, 0xffff0000, v119
	v_pk_add_f32 v[110:111], v[110:111], v[112:113]
	v_pk_add_f32 v[108:109], v[108:109], v[122:123]
	v_pk_add_f32 v[106:107], v[106:107], v[114:115]
	v_pk_add_f32 v[104:105], v[104:105], v[124:125]
	v_pk_add_f32 v[102:103], v[102:103], v[116:117]
	v_pk_add_f32 v[112:113], v[100:101], v[126:127]
	v_pk_add_f32 v[114:115], v[98:99], v[118:119]
	v_pk_add_f32 v[116:117], v[96:97], v[162:163]
	v_cvt_pk_bf16_f32 v96, v108, v109
	v_cvt_pk_bf16_f32 v97, v110, v111
	v_cvt_pk_bf16_f32 v98, v104, v105
	v_cvt_pk_bf16_f32 v99, v106, v107
	v_mul_f32_e32 v109, v109, v109
	v_mul_f32_e32 v111, v111, v111
	v_mul_f32_e32 v105, v105, v105
	v_mul_f32_e32 v107, v107, v107
	v_cvt_pk_bf16_f32 v100, v112, v113
	v_cvt_pk_bf16_f32 v101, v102, v103
	v_mul_f32_e32 v113, v113, v113
	v_mul_f32_e32 v103, v103, v103
	v_fmac_f32_e32 v109, v108, v108
	v_fmac_f32_e32 v111, v110, v110
	v_fmac_f32_e32 v105, v104, v104
	v_fmac_f32_e32 v107, v106, v106
	v_mul_f32_e32 v118, v117, v117
	v_mul_f32_e32 v119, v115, v115
	v_fmac_f32_e32 v113, v112, v112
	v_fmac_f32_e32 v103, v102, v102
	v_add_f32_e32 v104, v109, v111
	v_add_f32_e32 v105, v105, v107
	v_fmac_f32_e32 v118, v116, v116
	v_fmac_f32_e32 v119, v114, v114
	v_add_f32_e32 v103, v113, v103
	v_add_f32_e32 v104, v104, v105
	v_add_f32_e32 v102, v118, v119
	v_add_f32_e32 v103, v104, v103
	v_add_f32_e32 v104, v102, v103
	ds_swizzle_b32 v105, v104 offset:swizzle(SWAP,16)
	v_cvt_pk_bf16_f32 v102, v116, v117
	v_cvt_pk_bf16_f32 v103, v114, v115
	global_store_dwordx4 v[120:121], v[96:99], off
	global_store_dwordx4 v[120:121], v[100:103], off offset:256
	s_waitcnt lgkmcnt(0)
	v_add_f32_e32 v98, v104, v105
	v_mov_b32_e32 v99, v98
	s_nop 1
	v_permlane32_swap_b32_e32 v98, v99
	v_lshl_add_u64 v[96:97], v[156:157], 2, s[12:13]
	s_and_saveexec_b64 s[4:5], s[6:7]
	s_cbranch_execz .LBB0_542
	v_add_f32_e32 v98, v98, v99
	global_atomic_add_f32 v[96:97], v98, off offset:64
.LBB0_542:
	s_or_b64 exec, exec, s[4:5]
	v_or_b32_e32 v98, 32, v156
	v_ashrrev_i32_e32 v99, 31, v98
	v_lshlrev_b64 v[98:99], 11, v[98:99]
	v_lshl_add_u64 v[98:99], s[68:69], 0, v[98:99]
	v_lshl_add_u64 v[106:107], v[154:155], 1, v[98:99]
	s_nop 1
	v_mov_b32_e32 v98, v198
	v_mov_b32_e32 v99, v199
	v_mov_b32_e32 v100, v200
	v_mov_b32_e32 v101, v201
	s_nop 1
	v_mov_b32_e32 v102, v202
	v_mov_b32_e32 v103, v203
	v_mov_b32_e32 v104, v204
	v_mov_b32_e32 v105, v205
	v_lshlrev_b32_e32 v108, 16, v98
	v_and_b32_e32 v109, 0xffff0000, v98
	v_lshlrev_b32_e32 v98, 16, v99
	v_and_b32_e32 v99, 0xffff0000, v99
	v_lshlrev_b32_e32 v110, 16, v100
	v_and_b32_e32 v111, 0xffff0000, v100
	v_lshlrev_b32_e32 v100, 16, v101
	v_and_b32_e32 v101, 0xffff0000, v101
	v_lshlrev_b32_e32 v112, 16, v102
	v_and_b32_e32 v113, 0xffff0000, v102
	v_lshlrev_b32_e32 v102, 16, v103
	v_and_b32_e32 v103, 0xffff0000, v103
	v_lshlrev_b32_e32 v114, 16, v104
	v_and_b32_e32 v115, 0xffff0000, v104
	v_lshlrev_b32_e32 v104, 16, v105
	v_and_b32_e32 v105, 0xffff0000, v105
	v_pk_add_f32 v[94:95], v[94:95], v[98:99]
	v_pk_add_f32 v[92:93], v[92:93], v[108:109]
	v_pk_add_f32 v[90:91], v[90:91], v[100:101]
	v_pk_add_f32 v[88:89], v[88:89], v[110:111]
	v_pk_add_f32 v[86:87], v[86:87], v[102:103]
	v_pk_add_f32 v[98:99], v[84:85], v[112:113]
	v_pk_add_f32 v[100:101], v[82:83], v[104:105]
	v_pk_add_f32 v[102:103], v[80:81], v[114:115]
	v_cvt_pk_bf16_f32 v80, v92, v93
	v_cvt_pk_bf16_f32 v81, v94, v95
	v_cvt_pk_bf16_f32 v82, v88, v89
	v_cvt_pk_bf16_f32 v83, v90, v91
	v_mul_f32_e32 v93, v93, v93
	v_mul_f32_e32 v95, v95, v95
	v_mul_f32_e32 v89, v89, v89
	v_mul_f32_e32 v91, v91, v91
	v_cvt_pk_bf16_f32 v84, v98, v99
	v_cvt_pk_bf16_f32 v85, v86, v87
	v_mul_f32_e32 v99, v99, v99
	v_mul_f32_e32 v87, v87, v87
	v_fmac_f32_e32 v93, v92, v92
	v_fmac_f32_e32 v95, v94, v94
	v_fmac_f32_e32 v89, v88, v88
	v_fmac_f32_e32 v91, v90, v90
	v_mul_f32_e32 v104, v103, v103
	v_mul_f32_e32 v105, v101, v101
	v_fmac_f32_e32 v99, v98, v98
	v_fmac_f32_e32 v87, v86, v86
	v_add_f32_e32 v88, v93, v95
	v_add_f32_e32 v89, v89, v91
	v_fmac_f32_e32 v104, v102, v102
	v_fmac_f32_e32 v105, v100, v100
	v_add_f32_e32 v87, v99, v87
	v_add_f32_e32 v88, v88, v89
	v_add_f32_e32 v86, v104, v105
	v_add_f32_e32 v87, v88, v87
	v_add_f32_e32 v88, v86, v87
	ds_swizzle_b32 v89, v88 offset:swizzle(SWAP,16)
	v_cvt_pk_bf16_f32 v86, v102, v103
	v_cvt_pk_bf16_f32 v87, v100, v101
	global_store_dwordx4 v[106:107], v[80:83], off
	global_store_dwordx4 v[106:107], v[84:87], off offset:256
	s_waitcnt lgkmcnt(0)
	v_add_f32_e32 v80, v88, v89
	v_mov_b32_e32 v81, v80
	s_nop 1
	v_permlane32_swap_b32_e32 v80, v81
	s_and_saveexec_b64 s[4:5], s[6:7]
	s_cbranch_execz .LBB0_544
	v_add_f32_e32 v80, v80, v81
	global_atomic_add_f32 v[96:97], v80, off offset:128
; __device__ __forceinline__ unsigned pk2(float lo, float hi) { f32x2_t v = {lo, hi}; bf16x2_t b = __builtin_convertvector(v, bf16x2_t); return __builtin_bit_cast(unsigned, b); }
; __device__ __forceinline__ float bf_lo(unsigned w) { return __uint_as_float(w << 16); }
; __device__ __forceinline__ float bf_hi(unsigned w) { return __uint_as_float(w & 0xffff0000u); }
; __device__ __forceinline__ float xsum32(float v) { auto rr = __builtin_amdgcn_permlane32_swap(__float_as_uint(v), __float_as_uint(v), false, false); return __uint_as_float(rr[0]) + __uint_as_float(rr[1]); }
; __device__ __forceinline__ float xsum16(float v) { return v + __int_as_float(__builtin_amdgcn_ds_swizzle(__float_as_int(v), 0x401F)); }
;     __device__ __forceinline__ void operator()(const f32x4 (&acc)[2][2][4][2], const Unit& u, int wr, int wc, int fr, int fq) const {
;     ...
;             for (int m = 0; m < 4; ++m) { const size_t off = (size_t)(row0 + ai * HALF + m * 16) * DM + col0; float sq = 0.f;
; #pragma unroll
;                 for (int bj = 0; bj < 2; ++bj) { f32x4 o[2];
;                     if (bbase) { const u32x4 w = *(const u32x4*)(bbase + off + bj * HALF);
;                         o[0] = (f32x4){bf_lo(w.x), bf_hi(w.x), bf_lo(w.y), bf_hi(w.y)} + acc[ai][bj][m][0]; o[1] = (f32x4){bf_lo(w.z), bf_hi(w.z), bf_lo(w.w), bf_hi(w.w)} + acc[ai][bj][m][1]; }
;                     else { o[0] = *(const f32x4*)(base + off + bj * HALF) + acc[ai][bj][m][0]; o[1] = *(const f32x4*)(base + off + bj * HALF + 4) + acc[ai][bj][m][1]; }
; #pragma unroll
;                     for (int n = 0; n < 2; ++n) { if (out) *(f32x4*)(out + off + bj * HALF + 4 * n) = o[n];
;                         sq += (o[n][0] * o[n][0] + o[n][1] * o[n][1]) + (o[n][2] * o[n][2] + o[n][3] * o[n][3]); }
;                     if (xb) { u32x4 w; w.x = pk2(o[0][0], o[0][1]); w.y = pk2(o[0][2], o[0][3]); w.z = pk2(o[1][0], o[1][1]); w.w = pk2(o[1][2], o[1][3]); *(u32x4*)(xb + off + bj * HALF) = w; if (xb2) *(u32x4*)(xb2 + off + bj * HALF) = w; } }
;                 if (ss) { sq = xsum16(sq); sq = xsum32(sq); if (fq == 0) unsafeAtomicAdd(ss + row0 + ai * HALF + m * 16, sq); } }
.LBB0_544:
	s_or_b64 exec, exec, s[4:5]
	v_or_b32_e32 v80, 48, v156
	v_ashrrev_i32_e32 v81, 31, v80
	v_lshlrev_b64 v[80:81], 11, v[80:81]
	v_lshl_add_u64 v[80:81], s[68:69], 0, v[80:81]
	v_lshl_add_u64 v[88:89], v[154:155], 1, v[80:81]
	s_nop 1
	v_mov_b32_e32 v80, v208
	v_mov_b32_e32 v81, v209
	v_mov_b32_e32 v82, v210
	v_mov_b32_e32 v83, v211
	s_nop 1
	v_mov_b32_e32 v84, v212
	v_mov_b32_e32 v85, v213
	v_mov_b32_e32 v86, v214
	v_mov_b32_e32 v87, v215
	v_lshlrev_b32_e32 v90, 16, v80
	v_and_b32_e32 v91, 0xffff0000, v80
	v_lshlrev_b32_e32 v80, 16, v81
	v_and_b32_e32 v81, 0xffff0000, v81
	v_lshlrev_b32_e32 v92, 16, v82
	v_and_b32_e32 v93, 0xffff0000, v82
	v_lshlrev_b32_e32 v82, 16, v83
	v_and_b32_e32 v83, 0xffff0000, v83
	v_lshlrev_b32_e32 v94, 16, v84
	v_and_b32_e32 v95, 0xffff0000, v84
	v_lshlrev_b32_e32 v84, 16, v85
	v_and_b32_e32 v85, 0xffff0000, v85
	v_lshlrev_b32_e32 v98, 16, v86
	v_and_b32_e32 v99, 0xffff0000, v86
	v_lshlrev_b32_e32 v86, 16, v87
	v_and_b32_e32 v87, 0xffff0000, v87
	v_pk_add_f32 v[78:79], v[78:79], v[80:81]
	v_pk_add_f32 v[76:77], v[76:77], v[90:91]
	v_pk_add_f32 v[74:75], v[74:75], v[82:83]
	v_pk_add_f32 v[72:73], v[72:73], v[92:93]
	v_pk_add_f32 v[70:71], v[70:71], v[84:85]
	v_pk_add_f32 v[80:81], v[68:69], v[94:95]
	v_pk_add_f32 v[82:83], v[66:67], v[86:87]
	v_pk_add_f32 v[84:85], v[64:65], v[98:99]
	v_cvt_pk_bf16_f32 v64, v76, v77
	v_cvt_pk_bf16_f32 v65, v78, v79
	v_cvt_pk_bf16_f32 v66, v72, v73
	v_cvt_pk_bf16_f32 v67, v74, v75
	v_mul_f32_e32 v77, v77, v77
	v_mul_f32_e32 v79, v79, v79
	v_mul_f32_e32 v73, v73, v73
	v_mul_f32_e32 v75, v75, v75
	v_cvt_pk_bf16_f32 v68, v80, v81
	v_cvt_pk_bf16_f32 v69, v70, v71
	v_mul_f32_e32 v81, v81, v81
	v_mul_f32_e32 v71, v71, v71
	v_fmac_f32_e32 v77, v76, v76
	v_fmac_f32_e32 v79, v78, v78
	v_fmac_f32_e32 v73, v72, v72
	v_fmac_f32_e32 v75, v74, v74
	v_mul_f32_e32 v86, v85, v85
	v_mul_f32_e32 v87, v83, v83
	v_fmac_f32_e32 v81, v80, v80
	v_fmac_f32_e32 v71, v70, v70
	v_add_f32_e32 v72, v77, v79
	v_add_f32_e32 v73, v73, v75
	v_fmac_f32_e32 v86, v84, v84
	v_fmac_f32_e32 v87, v82, v82
	v_add_f32_e32 v71, v81, v71
	v_add_f32_e32 v72, v72, v73
	v_add_f32_e32 v70, v86, v87
	v_add_f32_e32 v71, v72, v71
	v_add_f32_e32 v72, v70, v71
	ds_swizzle_b32 v73, v72 offset:swizzle(SWAP,16)
	v_cvt_pk_bf16_f32 v70, v84, v85
	v_cvt_pk_bf16_f32 v71, v82, v83
	global_store_dwordx4 v[88:89], v[64:67], off
	global_store_dwordx4 v[88:89], v[68:71], off offset:256
	s_waitcnt lgkmcnt(0)
	v_add_f32_e32 v64, v72, v73
	v_mov_b32_e32 v65, v64
	s_nop 1
	v_permlane32_swap_b32_e32 v64, v65
	s_and_saveexec_b64 s[4:5], s[6:7]
	s_cbranch_execz .LBB0_546
	v_add_f32_e32 v64, v64, v65
	global_atomic_add_f32 v[96:97], v64, off offset:192
.LBB0_546:
	s_or_b64 exec, exec, s[4:5]
	v_add_co_u32_e32 v64, vcc, 0x40000, v152
	s_mov_b64 s[4:5], 0x40000
	s_nop 0
	v_addc_co_u32_e32 v65, vcc, 0, v153, vcc
	s_waitcnt vmcnt(0)
	s_nop 1
	v_mov_b32_e32 v68, v216
	v_mov_b32_e32 v69, v217
	v_mov_b32_e32 v70, v218
	v_mov_b32_e32 v71, v219
	v_lshl_add_u64 v[66:67], v[152:153], 0, s[4:5]
	s_nop 1
	v_mov_b32_e32 v72, v220
	v_mov_b32_e32 v73, v221
	v_mov_b32_e32 v74, v222
	v_mov_b32_e32 v75, v223
	v_lshlrev_b32_e32 v76, 16, v68
	v_and_b32_e32 v77, 0xffff0000, v68
	v_lshlrev_b32_e32 v68, 16, v69
	v_and_b32_e32 v69, 0xffff0000, v69
	v_lshlrev_b32_e32 v78, 16, v70
	v_and_b32_e32 v79, 0xffff0000, v70
	v_lshlrev_b32_e32 v70, 16, v71
	v_and_b32_e32 v71, 0xffff0000, v71
	v_lshlrev_b32_e32 v80, 16, v72
	v_and_b32_e32 v81, 0xffff0000, v72
	v_lshlrev_b32_e32 v72, 16, v73
	v_and_b32_e32 v73, 0xffff0000, v73
	v_lshlrev_b32_e32 v82, 16, v74
	v_and_b32_e32 v83, 0xffff0000, v74
	v_lshlrev_b32_e32 v74, 16, v75
	v_and_b32_e32 v75, 0xffff0000, v75
	v_pk_add_f32 v[62:63], v[62:63], v[68:69]
	v_pk_add_f32 v[60:61], v[60:61], v[76:77]
	v_pk_add_f32 v[58:59], v[58:59], v[70:71]
	v_pk_add_f32 v[56:57], v[56:57], v[78:79]
	v_pk_add_f32 v[54:55], v[54:55], v[72:73]
	v_pk_add_f32 v[68:69], v[52:53], v[80:81]
	v_pk_add_f32 v[70:71], v[50:51], v[74:75]
	v_pk_add_f32 v[72:73], v[48:49], v[82:83]
	v_cvt_pk_bf16_f32 v48, v60, v61
	v_cvt_pk_bf16_f32 v49, v62, v63
	v_cvt_pk_bf16_f32 v50, v56, v57
	v_cvt_pk_bf16_f32 v51, v58, v59
	v_mul_f32_e32 v61, v61, v61
	v_mul_f32_e32 v63, v63, v63
	v_mul_f32_e32 v57, v57, v57
	v_mul_f32_e32 v59, v59, v59
	v_cvt_pk_bf16_f32 v52, v68, v69
	v_cvt_pk_bf16_f32 v53, v54, v55
	v_mul_f32_e32 v69, v69, v69
	v_mul_f32_e32 v55, v55, v55
	v_fmac_f32_e32 v61, v60, v60
	v_fmac_f32_e32 v63, v62, v62
	v_fmac_f32_e32 v57, v56, v56
	v_fmac_f32_e32 v59, v58, v58
	v_mul_f32_e32 v74, v73, v73
	v_mul_f32_e32 v75, v71, v71
	v_fmac_f32_e32 v69, v68, v68
	v_fmac_f32_e32 v55, v54, v54
	v_add_f32_e32 v56, v61, v63
	v_add_f32_e32 v57, v57, v59
	v_fmac_f32_e32 v74, v72, v72
	v_fmac_f32_e32 v75, v70, v70
	v_add_f32_e32 v55, v69, v55
	v_add_f32_e32 v56, v56, v57
	v_add_f32_e32 v54, v74, v75
	v_add_f32_e32 v55, v56, v55
	v_add_f32_e32 v56, v54, v55
	ds_swizzle_b32 v57, v56 offset:swizzle(SWAP,16)
	v_cvt_pk_bf16_f32 v54, v72, v73
	v_cvt_pk_bf16_f32 v55, v70, v71
	global_store_dwordx4 v[64:65], v[48:51], off
	global_store_dwordx4 v[66:67], v[52:55], off offset:256
	s_waitcnt lgkmcnt(0)
	v_add_f32_e32 v48, v56, v57
	v_mov_b32_e32 v49, v48
	s_nop 1
	v_permlane32_swap_b32_e32 v48, v49
	s_and_saveexec_b64 s[4:5], s[6:7]
	s_cbranch_execz .LBB0_548
	v_add_f32_e32 v48, v48, v49
	global_atomic_add_f32 v[96:97], v48, off offset:512
; __device__ __forceinline__ unsigned pk2(float lo, float hi) { f32x2_t v = {lo, hi}; bf16x2_t b = __builtin_convertvector(v, bf16x2_t); return __builtin_bit_cast(unsigned, b); }
; __device__ __forceinline__ float bf_lo(unsigned w) { return __uint_as_float(w << 16); }
; __device__ __forceinline__ float bf_hi(unsigned w) { return __uint_as_float(w & 0xffff0000u); }
; __device__ __forceinline__ float xsum32(float v) { auto rr = __builtin_amdgcn_permlane32_swap(__float_as_uint(v), __float_as_uint(v), false, false); return __uint_as_float(rr[0]) + __uint_as_float(rr[1]); }
; __device__ __forceinline__ float xsum16(float v) { return v + __int_as_float(__builtin_amdgcn_ds_swizzle(__float_as_int(v), 0x401F)); }
;     __device__ __forceinline__ void operator()(const f32x4 (&acc)[2][2][4][2], const Unit& u, int wr, int wc, int fr, int fq) const {
;     ...
;             for (int m = 0; m < 4; ++m) { const size_t off = (size_t)(row0 + ai * HALF + m * 16) * DM + col0; float sq = 0.f;
; #pragma unroll
;                 for (int bj = 0; bj < 2; ++bj) { f32x4 o[2];
;                     if (bbase) { const u32x4 w = *(const u32x4*)(bbase + off + bj * HALF);
;                         o[0] = (f32x4){bf_lo(w.x), bf_hi(w.x), bf_lo(w.y), bf_hi(w.y)} + acc[ai][bj][m][0]; o[1] = (f32x4){bf_lo(w.z), bf_hi(w.z), bf_lo(w.w), bf_hi(w.w)} + acc[ai][bj][m][1]; }
;                     else { o[0] = *(const f32x4*)(base + off + bj * HALF) + acc[ai][bj][m][0]; o[1] = *(const f32x4*)(base + off + bj * HALF + 4) + acc[ai][bj][m][1]; }
; #pragma unroll
;                     for (int n = 0; n < 2; ++n) { if (out) *(f32x4*)(out + off + bj * HALF + 4 * n) = o[n];
;                         sq += (o[n][0] * o[n][0] + o[n][1] * o[n][1]) + (o[n][2] * o[n][2] + o[n][3] * o[n][3]); }
;                     if (xb) { u32x4 w; w.x = pk2(o[0][0], o[0][1]); w.y = pk2(o[0][2], o[0][3]); w.z = pk2(o[1][0], o[1][1]); w.w = pk2(o[1][2], o[1][3]); *(u32x4*)(xb + off + bj * HALF) = w; if (xb2) *(u32x4*)(xb2 + off + bj * HALF) = w; } }
;                 if (ss) { sq = xsum16(sq); sq = xsum32(sq); if (fq == 0) unsafeAtomicAdd(ss + row0 + ai * HALF + m * 16, sq); } }
.LBB0_548:
	s_or_b64 exec, exec, s[4:5]
	v_add_co_u32_e32 v48, vcc, 0x48000, v152
	s_mov_b64 s[4:5], 0x48000
	s_nop 0
	v_addc_co_u32_e32 v49, vcc, 0, v153, vcc
	s_nop 1
	v_mov_b32_e32 v52, v224
	v_mov_b32_e32 v53, v225
	v_mov_b32_e32 v54, v226
	v_mov_b32_e32 v55, v227
	v_lshl_add_u64 v[50:51], v[152:153], 0, s[4:5]
	s_nop 1
	v_mov_b32_e32 v56, v248
	v_mov_b32_e32 v57, v249
	v_mov_b32_e32 v58, v250
	v_mov_b32_e32 v59, v251
	v_lshlrev_b32_e32 v60, 16, v52
	v_and_b32_e32 v61, 0xffff0000, v52
	v_lshlrev_b32_e32 v52, 16, v53
	v_and_b32_e32 v53, 0xffff0000, v53
	v_lshlrev_b32_e32 v62, 16, v54
	v_and_b32_e32 v63, 0xffff0000, v54
	v_lshlrev_b32_e32 v54, 16, v55
	v_and_b32_e32 v55, 0xffff0000, v55
	v_lshlrev_b32_e32 v64, 16, v56
	v_and_b32_e32 v65, 0xffff0000, v56
	v_lshlrev_b32_e32 v56, 16, v57
	v_and_b32_e32 v57, 0xffff0000, v57
	v_lshlrev_b32_e32 v66, 16, v58
	v_and_b32_e32 v67, 0xffff0000, v58
	v_lshlrev_b32_e32 v58, 16, v59
	v_and_b32_e32 v59, 0xffff0000, v59
	v_pk_add_f32 v[46:47], v[46:47], v[52:53]
	v_pk_add_f32 v[44:45], v[44:45], v[60:61]
	v_pk_add_f32 v[42:43], v[42:43], v[54:55]
	v_pk_add_f32 v[40:41], v[40:41], v[62:63]
	v_pk_add_f32 v[38:39], v[38:39], v[56:57]
	v_pk_add_f32 v[52:53], v[36:37], v[64:65]
	v_pk_add_f32 v[54:55], v[34:35], v[58:59]
	v_pk_add_f32 v[56:57], v[32:33], v[66:67]
	v_cvt_pk_bf16_f32 v32, v44, v45
	v_cvt_pk_bf16_f32 v33, v46, v47
	v_cvt_pk_bf16_f32 v34, v40, v41
	v_cvt_pk_bf16_f32 v35, v42, v43
	v_mul_f32_e32 v45, v45, v45
	v_mul_f32_e32 v47, v47, v47
	v_mul_f32_e32 v41, v41, v41
	v_mul_f32_e32 v43, v43, v43
	v_cvt_pk_bf16_f32 v36, v52, v53
	v_cvt_pk_bf16_f32 v37, v38, v39
	v_mul_f32_e32 v53, v53, v53
	v_mul_f32_e32 v39, v39, v39
	v_fmac_f32_e32 v45, v44, v44
	v_fmac_f32_e32 v47, v46, v46
	v_fmac_f32_e32 v41, v40, v40
	v_fmac_f32_e32 v43, v42, v42
	v_mul_f32_e32 v58, v57, v57
	v_mul_f32_e32 v59, v55, v55
	v_fmac_f32_e32 v53, v52, v52
	v_fmac_f32_e32 v39, v38, v38
	v_add_f32_e32 v40, v45, v47
	v_add_f32_e32 v41, v41, v43
	v_fmac_f32_e32 v58, v56, v56
	v_fmac_f32_e32 v59, v54, v54
	v_add_f32_e32 v39, v53, v39
	v_add_f32_e32 v40, v40, v41
	v_add_f32_e32 v38, v58, v59
	v_add_f32_e32 v39, v40, v39
	v_add_f32_e32 v40, v38, v39
	ds_swizzle_b32 v41, v40 offset:swizzle(SWAP,16)
	v_cvt_pk_bf16_f32 v38, v56, v57
	v_cvt_pk_bf16_f32 v39, v54, v55
	global_store_dwordx4 v[48:49], v[32:35], off
	global_store_dwordx4 v[50:51], v[36:39], off offset:256
	s_waitcnt lgkmcnt(0)
	v_add_f32_e32 v32, v40, v41
	v_mov_b32_e32 v33, v32
	s_nop 1
	v_permlane32_swap_b32_e32 v32, v33
	s_and_saveexec_b64 s[4:5], s[6:7]
	s_cbranch_execz .LBB0_550
	v_add_f32_e32 v32, v32, v33
	global_atomic_add_f32 v[96:97], v32, off offset:576
; __device__ __forceinline__ unsigned pk2(float lo, float hi) { f32x2_t v = {lo, hi}; bf16x2_t b = __builtin_convertvector(v, bf16x2_t); return __builtin_bit_cast(unsigned, b); }
; __device__ __forceinline__ float bf_lo(unsigned w) { return __uint_as_float(w << 16); }
; __device__ __forceinline__ float bf_hi(unsigned w) { return __uint_as_float(w & 0xffff0000u); }
; __device__ __forceinline__ float xsum32(float v) { auto rr = __builtin_amdgcn_permlane32_swap(__float_as_uint(v), __float_as_uint(v), false, false); return __uint_as_float(rr[0]) + __uint_as_float(rr[1]); }
; __device__ __forceinline__ float xsum16(float v) { return v + __int_as_float(__builtin_amdgcn_ds_swizzle(__float_as_int(v), 0x401F)); }
;     __device__ __forceinline__ void operator()(const f32x4 (&acc)[2][2][4][2], const Unit& u, int wr, int wc, int fr, int fq) const {
;     ...
;             for (int m = 0; m < 4; ++m) { const size_t off = (size_t)(row0 + ai * HALF + m * 16) * DM + col0; float sq = 0.f;
; #pragma unroll
;                 for (int bj = 0; bj < 2; ++bj) { f32x4 o[2];
;                     if (bbase) { const u32x4 w = *(const u32x4*)(bbase + off + bj * HALF);
;                         o[0] = (f32x4){bf_lo(w.x), bf_hi(w.x), bf_lo(w.y), bf_hi(w.y)} + acc[ai][bj][m][0]; o[1] = (f32x4){bf_lo(w.z), bf_hi(w.z), bf_lo(w.w), bf_hi(w.w)} + acc[ai][bj][m][1]; }
;                     else { o[0] = *(const f32x4*)(base + off + bj * HALF) + acc[ai][bj][m][0]; o[1] = *(const f32x4*)(base + off + bj * HALF + 4) + acc[ai][bj][m][1]; }
; #pragma unroll
;                     for (int n = 0; n < 2; ++n) { if (out) *(f32x4*)(out + off + bj * HALF + 4 * n) = o[n];
;                         sq += (o[n][0] * o[n][0] + o[n][1] * o[n][1]) + (o[n][2] * o[n][2] + o[n][3] * o[n][3]); }
;                     if (xb) { u32x4 w; w.x = pk2(o[0][0], o[0][1]); w.y = pk2(o[0][2], o[0][3]); w.z = pk2(o[1][0], o[1][1]); w.w = pk2(o[1][2], o[1][3]); *(u32x4*)(xb + off + bj * HALF) = w; if (xb2) *(u32x4*)(xb2 + off + bj * HALF) = w; } }
;                 if (ss) { sq = xsum16(sq); sq = xsum32(sq); if (fq == 0) unsafeAtomicAdd(ss + row0 + ai * HALF + m * 16, sq); } }
.LBB0_550:
	s_or_b64 exec, exec, s[4:5]
	v_add_co_u32_e32 v32, vcc, 0x50000, v152
	s_mov_b64 s[4:5], 0x50000
	s_nop 0
	v_addc_co_u32_e32 v33, vcc, 0, v153, vcc
	s_nop 1
	v_mov_b32_e32 v36, v178
	v_mov_b32_e32 v37, v179
	v_mov_b32_e32 v38, v180
	v_mov_b32_e32 v39, v181
	v_lshl_add_u64 v[34:35], v[152:153], 0, s[4:5]
	s_nop 1
	v_mov_b32_e32 v40, v182
	v_mov_b32_e32 v41, v183
	v_mov_b32_e32 v42, v184
	v_mov_b32_e32 v43, v185
	v_lshlrev_b32_e32 v44, 16, v36
	v_and_b32_e32 v45, 0xffff0000, v36
	v_lshlrev_b32_e32 v36, 16, v37
	v_and_b32_e32 v37, 0xffff0000, v37
	v_lshlrev_b32_e32 v46, 16, v38
	v_and_b32_e32 v47, 0xffff0000, v38
	v_lshlrev_b32_e32 v38, 16, v39
	v_and_b32_e32 v39, 0xffff0000, v39
	v_lshlrev_b32_e32 v48, 16, v40
	v_and_b32_e32 v49, 0xffff0000, v40
	v_lshlrev_b32_e32 v40, 16, v41
	v_and_b32_e32 v41, 0xffff0000, v41
	v_lshlrev_b32_e32 v50, 16, v42
	v_and_b32_e32 v51, 0xffff0000, v42
	v_lshlrev_b32_e32 v42, 16, v43
	v_and_b32_e32 v43, 0xffff0000, v43
	v_pk_add_f32 v[30:31], v[30:31], v[36:37]
	v_pk_add_f32 v[28:29], v[28:29], v[44:45]
	v_pk_add_f32 v[26:27], v[26:27], v[38:39]
	v_pk_add_f32 v[24:25], v[24:25], v[46:47]
	v_pk_add_f32 v[22:23], v[22:23], v[40:41]
	v_pk_add_f32 v[36:37], v[20:21], v[48:49]
	v_pk_add_f32 v[38:39], v[18:19], v[42:43]
	v_pk_add_f32 v[40:41], v[16:17], v[50:51]
	v_cvt_pk_bf16_f32 v16, v28, v29
	v_cvt_pk_bf16_f32 v17, v30, v31
	v_cvt_pk_bf16_f32 v18, v24, v25
	v_cvt_pk_bf16_f32 v19, v26, v27
	v_mul_f32_e32 v29, v29, v29
	v_mul_f32_e32 v31, v31, v31
	v_mul_f32_e32 v25, v25, v25
	v_mul_f32_e32 v27, v27, v27
	v_cvt_pk_bf16_f32 v20, v36, v37
	v_cvt_pk_bf16_f32 v21, v22, v23
	v_mul_f32_e32 v37, v37, v37
	v_mul_f32_e32 v23, v23, v23
	v_fmac_f32_e32 v29, v28, v28
	v_fmac_f32_e32 v31, v30, v30
	v_fmac_f32_e32 v25, v24, v24
	v_fmac_f32_e32 v27, v26, v26
	v_mul_f32_e32 v42, v41, v41
	v_mul_f32_e32 v43, v39, v39
	v_fmac_f32_e32 v37, v36, v36
	v_fmac_f32_e32 v23, v22, v22
	v_add_f32_e32 v24, v29, v31
	v_add_f32_e32 v25, v25, v27
	v_fmac_f32_e32 v42, v40, v40
	v_fmac_f32_e32 v43, v38, v38
	v_add_f32_e32 v23, v37, v23
	v_add_f32_e32 v24, v24, v25
	v_add_f32_e32 v22, v42, v43
	v_add_f32_e32 v23, v24, v23
	v_add_f32_e32 v24, v22, v23
	ds_swizzle_b32 v25, v24 offset:swizzle(SWAP,16)
	v_cvt_pk_bf16_f32 v22, v40, v41
	v_cvt_pk_bf16_f32 v23, v38, v39
	global_store_dwordx4 v[32:33], v[16:19], off
	global_store_dwordx4 v[34:35], v[20:23], off offset:256
	s_waitcnt lgkmcnt(0)
	v_add_f32_e32 v16, v24, v25
	v_mov_b32_e32 v17, v16
	s_nop 1
	v_permlane32_swap_b32_e32 v16, v17
	s_and_saveexec_b64 s[4:5], s[6:7]
	s_cbranch_execz .LBB0_552
	v_add_f32_e32 v16, v16, v17
	global_atomic_add_f32 v[96:97], v16, off offset:640
.LBB0_552:
	s_or_b64 exec, exec, s[4:5]
	v_add_co_u32_e32 v16, vcc, 0x58000, v152
	s_mov_b64 s[4:5], 0x58000
	s_nop 0
	v_addc_co_u32_e32 v17, vcc, 0, v153, vcc
	s_nop 1
	v_mov_b32_e32 v20, v186
	v_mov_b32_e32 v21, v187
	v_mov_b32_e32 v22, v188
	v_mov_b32_e32 v23, v189
	v_lshl_add_u64 v[18:19], v[152:153], 0, s[4:5]
	s_nop 1
	v_mov_b32_e32 v24, v194
	v_mov_b32_e32 v25, v195
	v_mov_b32_e32 v26, v196
	v_mov_b32_e32 v27, v197
	v_lshlrev_b32_e32 v28, 16, v20
	v_and_b32_e32 v29, 0xffff0000, v20
	v_lshlrev_b32_e32 v20, 16, v21
	v_and_b32_e32 v21, 0xffff0000, v21
	v_lshlrev_b32_e32 v30, 16, v22
	v_and_b32_e32 v31, 0xffff0000, v22
	v_lshlrev_b32_e32 v22, 16, v23
	v_and_b32_e32 v23, 0xffff0000, v23
	v_lshlrev_b32_e32 v32, 16, v24
	v_and_b32_e32 v33, 0xffff0000, v24
	v_lshlrev_b32_e32 v24, 16, v25
	v_and_b32_e32 v25, 0xffff0000, v25
	v_lshlrev_b32_e32 v34, 16, v26
	v_and_b32_e32 v35, 0xffff0000, v26
	v_lshlrev_b32_e32 v26, 16, v27
	v_and_b32_e32 v27, 0xffff0000, v27
	v_pk_add_f32 v[14:15], v[14:15], v[20:21]
	v_pk_add_f32 v[12:13], v[12:13], v[28:29]
	v_pk_add_f32 v[10:11], v[10:11], v[22:23]
	v_pk_add_f32 v[8:9], v[8:9], v[30:31]
	v_pk_add_f32 v[6:7], v[6:7], v[24:25]
	v_pk_add_f32 v[20:21], v[4:5], v[32:33]
	v_pk_add_f32 v[22:23], v[2:3], v[26:27]
	v_pk_add_f32 v[24:25], v[0:1], v[34:35]
	v_cvt_pk_bf16_f32 v0, v12, v13
	v_cvt_pk_bf16_f32 v1, v14, v15
	v_cvt_pk_bf16_f32 v2, v8, v9
	v_cvt_pk_bf16_f32 v3, v10, v11
	v_mul_f32_e32 v13, v13, v13
	v_mul_f32_e32 v15, v15, v15
	v_mul_f32_e32 v9, v9, v9
	v_mul_f32_e32 v11, v11, v11
	v_cvt_pk_bf16_f32 v4, v20, v21
	v_cvt_pk_bf16_f32 v5, v6, v7
	v_mul_f32_e32 v21, v21, v21
	v_mul_f32_e32 v7, v7, v7
	v_fmac_f32_e32 v13, v12, v12
	v_fmac_f32_e32 v15, v14, v14
	v_fmac_f32_e32 v9, v8, v8
	v_fmac_f32_e32 v11, v10, v10
	v_mul_f32_e32 v26, v25, v25
	v_mul_f32_e32 v27, v23, v23
	v_fmac_f32_e32 v21, v20, v20
	v_fmac_f32_e32 v7, v6, v6
	v_add_f32_e32 v8, v13, v15
	v_add_f32_e32 v9, v9, v11
	v_fmac_f32_e32 v26, v24, v24
	v_fmac_f32_e32 v27, v22, v22
	v_add_f32_e32 v7, v21, v7
	v_add_f32_e32 v8, v8, v9
	v_add_f32_e32 v6, v26, v27
	v_add_f32_e32 v7, v8, v7
	v_add_f32_e32 v8, v6, v7
	ds_swizzle_b32 v9, v8 offset:swizzle(SWAP,16)
	v_cvt_pk_bf16_f32 v6, v24, v25
	v_cvt_pk_bf16_f32 v7, v22, v23
	global_store_dwordx4 v[16:17], v[0:3], off
	global_store_dwordx4 v[18:19], v[4:7], off offset:256
	s_waitcnt lgkmcnt(0)
	v_add_f32_e32 v0, v8, v9
	v_mov_b32_e32 v1, v0
	s_nop 1
	v_permlane32_swap_b32_e32 v0, v1
	s_and_saveexec_b64 s[4:5], s[6:7]
	s_cbranch_execz .LBB0_554
	v_add_f32_e32 v0, v0, v1
	global_atomic_add_f32 v[96:97], v0, off offset:704

; __device__ __forceinline__ unsigned pk2(float lo, float hi) { f32x2_t v = {lo, hi}; bf16x2_t b = __builtin_convertvector(v, bf16x2_t); return __builtin_bit_cast(unsigned, b); }
; __device__ __forceinline__ float bf_lo(unsigned w) { return __uint_as_float(w << 16); }
; __device__ __forceinline__ float bf_hi(unsigned w) { return __uint_as_float(w & 0xffff0000u); }
;     __device__ __forceinline__ void operator()(const f32x4 (&acc)[2][2][4][2], const Unit& u, int wr, int wc, int fr, int fq) const {
;     ...
;             for (int m = 0; m < 4; ++m) { const size_t off = (size_t)(row0 + ai * HALF + m * 16) * DM + col0; float sq = 0.f;
; #pragma unroll
;                 for (int bj = 0; bj < 2; ++bj) { f32x4 o[2];
;                     if (bbase) { const u32x4 w = *(const u32x4*)(bbase + off + bj * HALF);
;                         o[0] = (f32x4){bf_lo(w.x), bf_hi(w.x), bf_lo(w.y), bf_hi(w.y)} + acc[ai][bj][m][0]; o[1] = (f32x4){bf_lo(w.z), bf_hi(w.z), bf_lo(w.w), bf_hi(w.w)} + acc[ai][bj][m][1]; }
;                     else { o[0] = *(const f32x4*)(base + off + bj * HALF) + acc[ai][bj][m][0]; o[1] = *(const f32x4*)(base + off + bj * HALF + 4) + acc[ai][bj][m][1]; }
; #pragma unroll
;                     for (int n = 0; n < 2; ++n) { if (out) *(f32x4*)(out + off + bj * HALF + 4 * n) = o[n];
;                         sq += (o[n][0] * o[n][0] + o[n][1] * o[n][1]) + (o[n][2] * o[n][2] + o[n][3] * o[n][3]); }
;                     if (xb) { u32x4 w; w.x = pk2(o[0][0], o[0][1]); w.y = pk2(o[0][2], o[0][3]); w.z = pk2(o[1][0], o[1][1]); w.w = pk2(o[1][2], o[1][3]); *(u32x4*)(xb + off + bj * HALF) = w; if (xb2) *(u32x4*)(xb2 + off + bj * HALF) = w; } }
.LBB0_696:
	v_lshl_add_u32 v156, s47, 8, v131
	v_lshl_or_b32 v154, s46, 8, v166
	v_ashrrev_i32_e32 v157, 31, v156
	v_ashrrev_i32_e32 v155, 31, v154
	v_lshlrev_b64 v[152:153], 10, v[156:157]
	v_lshl_add_u64 v[152:153], v[152:153], 0, v[154:155]
	v_lshl_add_u64 v[158:159], v[152:153], 1, s[68:69]
	v_mov_b32_e32 v248, v158
	v_mov_b32_e32 v249, v159
	global_load_dwordx4 v[174:177], v[248:249], off
	global_load_dwordx4 v[178:181], v[248:249], off offset:256
	s_mov_b32 s98, 0x8000
	s_mov_b32 s99, 0
	v_lshl_add_u64 v[250:251], v[248:249], 0, s[98:99]
	global_load_dwordx4 v[182:185], v[250:251], off
	global_load_dwordx4 v[186:189], v[250:251], off offset:256
	s_mov_b32 s98, 0x10000
	s_mov_b32 s99, 0
	v_lshl_add_u64 v[250:251], v[248:249], 0, s[98:99]
	global_load_dwordx4 v[194:197], v[250:251], off
	global_load_dwordx4 v[198:201], v[250:251], off offset:256
	s_mov_b32 s98, 0x18000
	s_mov_b32 s99, 0
	v_lshl_add_u64 v[250:251], v[248:249], 0, s[98:99]
	global_load_dwordx4 v[202:205], v[250:251], off
	global_load_dwordx4 v[208:211], v[250:251], off offset:256
	s_waitcnt vmcnt(0)
	s_nop 1
	v_mov_b32_e32 v160, v174
	v_mov_b32_e32 v161, v175
	v_mov_b32_e32 v162, v176
	v_mov_b32_e32 v163, v177
	v_cndmask_b32_e64 v164, 0, 1, s[18:19]
	v_cmp_ne_u32_e64 s[8:9], 1, v164
	v_readlane_b32 s64, v247, 39
	v_readlane_b32 s78, v247, 53
	v_readlane_b32 s79, v247, 54
	s_andn2_b64 vcc, exec, s[18:19]
	v_readlane_b32 s65, v247, 40
	v_readlane_b32 s66, v247, 41
	v_readlane_b32 s67, v247, 42
	v_readlane_b32 s68, v247, 43
	v_readlane_b32 s69, v247, 44
	v_readlane_b32 s70, v247, 45
	v_readlane_b32 s71, v247, 46
	v_readlane_b32 s72, v247, 47
	v_readlane_b32 s73, v247, 48
	v_readlane_b32 s74, v247, 49
	v_readlane_b32 s75, v247, 50
	v_readlane_b32 s76, v247, 51
	v_readlane_b32 s77, v247, 52
	v_lshlrev_b32_e32 v164, 16, v160
	v_and_b32_e32 v165, 0xffff0000, v160
	v_lshlrev_b32_e32 v160, 16, v161
	v_and_b32_e32 v161, 0xffff0000, v161
	v_lshlrev_b32_e32 v170, 16, v162
	v_and_b32_e32 v171, 0xffff0000, v162
	v_lshlrev_b32_e32 v172, 16, v163
	v_and_b32_e32 v173, 0xffff0000, v163
	v_pk_add_f32 v[160:161], v[126:127], v[160:161]
	v_pk_add_f32 v[162:163], v[124:125], v[164:165]
	v_pk_add_f32 v[124:125], v[122:123], v[172:173]
	v_pk_add_f32 v[126:127], v[120:121], v[170:171]
	v_cvt_pk_bf16_f32 v120, v162, v163
	v_cvt_pk_bf16_f32 v121, v160, v161
	v_cvt_pk_bf16_f32 v122, v126, v127
	v_cvt_pk_bf16_f32 v123, v124, v125
	v_lshl_add_u64 v[164:165], v[152:153], 1, s[78:79]
	global_store_dwordx4 v[158:159], v[120:123], off
	s_cbranch_vccnz .LBB0_698
	global_store_dwordx4 v[164:165], v[120:123], off
.LBB0_698:
	s_nop 1
	v_mov_b32_e32 v120, v178
	v_mov_b32_e32 v121, v179
	v_mov_b32_e32 v122, v180
	v_mov_b32_e32 v123, v181
	s_and_b64 vcc, exec, s[8:9]
	v_lshlrev_b32_e32 v170, 16, v120
	v_and_b32_e32 v171, 0xffff0000, v120
	v_lshlrev_b32_e32 v120, 16, v121
	v_and_b32_e32 v121, 0xffff0000, v121
	v_lshlrev_b32_e32 v172, 16, v122
	v_and_b32_e32 v173, 0xffff0000, v122
	v_lshlrev_b32_e32 v122, 16, v123
	v_and_b32_e32 v123, 0xffff0000, v123
	v_pk_add_f32 v[118:119], v[118:119], v[120:121]
	v_pk_add_f32 v[120:121], v[116:117], v[170:171]
	v_pk_add_f32 v[116:117], v[114:115], v[122:123]
	v_pk_add_f32 v[122:123], v[112:113], v[172:173]
	v_cvt_pk_bf16_f32 v112, v120, v121
	v_cvt_pk_bf16_f32 v113, v118, v119
	v_cvt_pk_bf16_f32 v114, v122, v123
	v_cvt_pk_bf16_f32 v115, v116, v117
	global_store_dwordx4 v[158:159], v[112:115], off offset:256
	s_cbranch_vccnz .LBB0_700
	global_store_dwordx4 v[164:165], v[112:115], off offset:256

; __device__ __forceinline__ unsigned pk2(float lo, float hi) { f32x2_t v = {lo, hi}; bf16x2_t b = __builtin_convertvector(v, bf16x2_t); return __builtin_bit_cast(unsigned, b); }
; __device__ __forceinline__ float bf_lo(unsigned w) { return __uint_as_float(w << 16); }
; __device__ __forceinline__ float bf_hi(unsigned w) { return __uint_as_float(w & 0xffff0000u); }
;     __device__ __forceinline__ void operator()(const f32x4 (&acc)[2][2][4][2], const Unit& u, int wr, int wc, int fr, int fq) const {
;     ...
;             for (int m = 0; m < 4; ++m) { const size_t off = (size_t)(row0 + ai * HALF + m * 16) * DM + col0; float sq = 0.f;
; #pragma unroll
;                 for (int bj = 0; bj < 2; ++bj) { f32x4 o[2];
;                     if (bbase) { const u32x4 w = *(const u32x4*)(bbase + off + bj * HALF);
;                         o[0] = (f32x4){bf_lo(w.x), bf_hi(w.x), bf_lo(w.y), bf_hi(w.y)} + acc[ai][bj][m][0]; o[1] = (f32x4){bf_lo(w.z), bf_hi(w.z), bf_lo(w.w), bf_hi(w.w)} + acc[ai][bj][m][1]; }
;                     else { o[0] = *(const f32x4*)(base + off + bj * HALF) + acc[ai][bj][m][0]; o[1] = *(const f32x4*)(base + off + bj * HALF + 4) + acc[ai][bj][m][1]; }
; #pragma unroll
;                     for (int n = 0; n < 2; ++n) { if (out) *(f32x4*)(out + off + bj * HALF + 4 * n) = o[n];
;                         sq += (o[n][0] * o[n][0] + o[n][1] * o[n][1]) + (o[n][2] * o[n][2] + o[n][3] * o[n][3]); }
;                     if (xb) { u32x4 w; w.x = pk2(o[0][0], o[0][1]); w.y = pk2(o[0][2], o[0][3]); w.z = pk2(o[1][0], o[1][1]); w.w = pk2(o[1][2], o[1][3]); *(u32x4*)(xb + off + bj * HALF) = w; if (xb2) *(u32x4*)(xb2 + off + bj * HALF) = w; } }
.LBB0_702:
	s_or_b64 exec, exec, s[24:25]
	v_or_b32_e32 v114, 16, v156
	v_ashrrev_i32_e32 v115, 31, v114
	v_lshlrev_b64 v[114:115], 10, v[114:115]
	v_lshl_add_u64 v[120:121], v[114:115], 0, v[154:155]
	v_lshl_add_u64 v[114:115], v[120:121], 1, s[28:29]
	s_nop 1
	v_mov_b32_e32 v116, v182
	v_mov_b32_e32 v117, v183
	v_mov_b32_e32 v118, v184
	v_mov_b32_e32 v119, v185
	v_readlane_b32 s64, v247, 39
	v_readlane_b32 s78, v247, 53
	v_readlane_b32 s79, v247, 54
	s_and_b64 vcc, exec, s[8:9]
	v_readlane_b32 s65, v247, 40
	v_lshl_add_u64 v[120:121], v[120:121], 1, s[78:79]
	v_readlane_b32 s66, v247, 41
	v_readlane_b32 s67, v247, 42
	v_readlane_b32 s68, v247, 43
	v_readlane_b32 s69, v247, 44
	v_readlane_b32 s70, v247, 45
	v_readlane_b32 s71, v247, 46
	v_readlane_b32 s72, v247, 47
	v_readlane_b32 s73, v247, 48
	v_readlane_b32 s74, v247, 49
	v_readlane_b32 s75, v247, 50
	v_readlane_b32 s76, v247, 51
	v_readlane_b32 s77, v247, 52
	v_lshlrev_b32_e32 v122, 16, v116
	v_and_b32_e32 v123, 0xffff0000, v116
	v_lshlrev_b32_e32 v116, 16, v117
	v_and_b32_e32 v117, 0xffff0000, v117
	v_lshlrev_b32_e32 v124, 16, v118
	v_and_b32_e32 v125, 0xffff0000, v118
	v_lshlrev_b32_e32 v126, 16, v119
	v_and_b32_e32 v127, 0xffff0000, v119
	v_pk_add_f32 v[116:117], v[110:111], v[116:117]
	v_pk_add_f32 v[118:119], v[108:109], v[122:123]
	v_pk_add_f32 v[108:109], v[106:107], v[126:127]
	v_pk_add_f32 v[110:111], v[104:105], v[124:125]
	v_cvt_pk_bf16_f32 v104, v118, v119
	v_cvt_pk_bf16_f32 v105, v116, v117
	v_cvt_pk_bf16_f32 v106, v110, v111
	v_cvt_pk_bf16_f32 v107, v108, v109
	global_store_dwordx4 v[114:115], v[104:107], off
	s_cbranch_vccnz .LBB0_704
	global_store_dwordx4 v[120:121], v[104:107], off
.LBB0_704:
	s_nop 1
	v_mov_b32_e32 v104, v186
	v_mov_b32_e32 v105, v187
	v_mov_b32_e32 v106, v188
	v_mov_b32_e32 v107, v189
	s_mov_b32 s98, 0x40000
	s_mov_b32 s99, 0
	v_lshl_add_u64 v[250:251], v[248:249], 0, s[98:99]
	global_load_dwordx4 v[212:215], v[250:251], off
	global_load_dwordx4 v[216:219], v[250:251], off offset:256
	s_mov_b32 s98, 0x48000
	s_mov_b32 s99, 0
	v_lshl_add_u64 v[250:251], v[248:249], 0, s[98:99]
	global_load_dwordx4 v[220:223], v[250:251], off
	global_load_dwordx4 v[224:227], v[250:251], off offset:256
	s_mov_b32 s98, 0x50000
	s_mov_b32 s99, 0
	v_lshl_add_u64 v[250:251], v[248:249], 0, s[98:99]
	global_load_dwordx4 v[174:177], v[250:251], off
	global_load_dwordx4 v[178:181], v[250:251], off offset:256
	s_mov_b32 s98, 0x58000
	s_mov_b32 s99, 0
	v_lshl_add_u64 v[250:251], v[248:249], 0, s[98:99]
	global_load_dwordx4 v[182:185], v[250:251], off
	global_load_dwordx4 v[186:189], v[250:251], off offset:256
	s_and_b64 vcc, exec, s[8:9]
	v_lshlrev_b32_e32 v122, 16, v104
	v_and_b32_e32 v123, 0xffff0000, v104
	v_lshlrev_b32_e32 v104, 16, v105
	v_and_b32_e32 v105, 0xffff0000, v105
	v_lshlrev_b32_e32 v124, 16, v106
	v_and_b32_e32 v125, 0xffff0000, v106
	v_lshlrev_b32_e32 v106, 16, v107
	v_and_b32_e32 v107, 0xffff0000, v107
	v_pk_add_f32 v[102:103], v[102:103], v[104:105]
	v_pk_add_f32 v[104:105], v[100:101], v[122:123]
	v_pk_add_f32 v[100:101], v[98:99], v[106:107]
	v_pk_add_f32 v[106:107], v[96:97], v[124:125]
	v_cvt_pk_bf16_f32 v96, v104, v105
	v_cvt_pk_bf16_f32 v97, v102, v103
	v_cvt_pk_bf16_f32 v98, v106, v107
	v_cvt_pk_bf16_f32 v99, v100, v101
	global_store_dwordx4 v[114:115], v[96:99], off offset:256
	s_cbranch_vccnz .LBB0_706
	global_store_dwordx4 v[120:121], v[96:99], off offset:256

; __device__ __forceinline__ unsigned pk2(float lo, float hi) { f32x2_t v = {lo, hi}; bf16x2_t b = __builtin_convertvector(v, bf16x2_t); return __builtin_bit_cast(unsigned, b); }
; __device__ __forceinline__ float bf_lo(unsigned w) { return __uint_as_float(w << 16); }
; __device__ __forceinline__ float bf_hi(unsigned w) { return __uint_as_float(w & 0xffff0000u); }
;     __device__ __forceinline__ void operator()(const f32x4 (&acc)[2][2][4][2], const Unit& u, int wr, int wc, int fr, int fq) const {
;     ...
;             for (int m = 0; m < 4; ++m) { const size_t off = (size_t)(row0 + ai * HALF + m * 16) * DM + col0; float sq = 0.f;
; #pragma unroll
;                 for (int bj = 0; bj < 2; ++bj) { f32x4 o[2];
;                     if (bbase) { const u32x4 w = *(const u32x4*)(bbase + off + bj * HALF);
;                         o[0] = (f32x4){bf_lo(w.x), bf_hi(w.x), bf_lo(w.y), bf_hi(w.y)} + acc[ai][bj][m][0]; o[1] = (f32x4){bf_lo(w.z), bf_hi(w.z), bf_lo(w.w), bf_hi(w.w)} + acc[ai][bj][m][1]; }
;                     else { o[0] = *(const f32x4*)(base + off + bj * HALF) + acc[ai][bj][m][0]; o[1] = *(const f32x4*)(base + off + bj * HALF + 4) + acc[ai][bj][m][1]; }
; #pragma unroll
;                     for (int n = 0; n < 2; ++n) { if (out) *(f32x4*)(out + off + bj * HALF + 4 * n) = o[n];
;                         sq += (o[n][0] * o[n][0] + o[n][1] * o[n][1]) + (o[n][2] * o[n][2] + o[n][3] * o[n][3]); }
;                     if (xb) { u32x4 w; w.x = pk2(o[0][0], o[0][1]); w.y = pk2(o[0][2], o[0][3]); w.z = pk2(o[1][0], o[1][1]); w.w = pk2(o[1][2], o[1][3]); *(u32x4*)(xb + off + bj * HALF) = w; if (xb2) *(u32x4*)(xb2 + off + bj * HALF) = w; } }
.LBB0_708:
	s_or_b64 exec, exec, s[24:25]
	v_or_b32_e32 v96, 32, v156
	v_ashrrev_i32_e32 v97, 31, v96
	v_lshlrev_b64 v[96:97], 10, v[96:97]
	v_lshl_add_u64 v[102:103], v[96:97], 0, v[154:155]
	v_lshl_add_u64 v[96:97], v[102:103], 1, s[28:29]
	s_nop 1
	v_mov_b32_e32 v98, v194
	v_mov_b32_e32 v99, v195
	v_mov_b32_e32 v100, v196
	v_mov_b32_e32 v101, v197
	v_readlane_b32 s64, v247, 39
	v_readlane_b32 s78, v247, 53
	v_readlane_b32 s79, v247, 54
	s_and_b64 vcc, exec, s[8:9]
	v_readlane_b32 s65, v247, 40
	v_lshl_add_u64 v[102:103], v[102:103], 1, s[78:79]
	v_readlane_b32 s66, v247, 41
	v_readlane_b32 s67, v247, 42
	v_readlane_b32 s68, v247, 43
	v_readlane_b32 s69, v247, 44
	v_readlane_b32 s70, v247, 45
	v_readlane_b32 s71, v247, 46
	v_readlane_b32 s72, v247, 47
	v_readlane_b32 s73, v247, 48
	v_readlane_b32 s74, v247, 49
	v_readlane_b32 s75, v247, 50
	v_readlane_b32 s76, v247, 51
	v_readlane_b32 s77, v247, 52
	v_lshlrev_b32_e32 v104, 16, v98
	v_and_b32_e32 v105, 0xffff0000, v98
	v_lshlrev_b32_e32 v98, 16, v99
	v_and_b32_e32 v99, 0xffff0000, v99
	v_lshlrev_b32_e32 v106, 16, v100
	v_and_b32_e32 v107, 0xffff0000, v100
	v_lshlrev_b32_e32 v108, 16, v101
	v_and_b32_e32 v109, 0xffff0000, v101
	v_pk_add_f32 v[98:99], v[94:95], v[98:99]
	v_pk_add_f32 v[100:101], v[92:93], v[104:105]
	v_pk_add_f32 v[92:93], v[90:91], v[108:109]
	v_pk_add_f32 v[94:95], v[88:89], v[106:107]
	v_cvt_pk_bf16_f32 v88, v100, v101
	v_cvt_pk_bf16_f32 v89, v98, v99
	v_cvt_pk_bf16_f32 v90, v94, v95
	v_cvt_pk_bf16_f32 v91, v92, v93
	global_store_dwordx4 v[96:97], v[88:91], off
	s_cbranch_vccnz .LBB0_710
	global_store_dwordx4 v[102:103], v[88:91], off
.LBB0_710:
	s_nop 1
	v_mov_b32_e32 v88, v198
	v_mov_b32_e32 v89, v199
	v_mov_b32_e32 v90, v200
	v_mov_b32_e32 v91, v201
	s_and_b64 vcc, exec, s[8:9]
	v_lshlrev_b32_e32 v104, 16, v88
	v_and_b32_e32 v105, 0xffff0000, v88
	v_lshlrev_b32_e32 v88, 16, v89
	v_and_b32_e32 v89, 0xffff0000, v89
	v_lshlrev_b32_e32 v106, 16, v90
	v_and_b32_e32 v107, 0xffff0000, v90
	v_lshlrev_b32_e32 v90, 16, v91
	v_and_b32_e32 v91, 0xffff0000, v91
	v_pk_add_f32 v[86:87], v[86:87], v[88:89]
	v_pk_add_f32 v[88:89], v[84:85], v[104:105]
	v_pk_add_f32 v[84:85], v[82:83], v[90:91]
	v_pk_add_f32 v[90:91], v[80:81], v[106:107]
	v_cvt_pk_bf16_f32 v80, v88, v89
	v_cvt_pk_bf16_f32 v81, v86, v87
	v_cvt_pk_bf16_f32 v82, v90, v91
	v_cvt_pk_bf16_f32 v83, v84, v85
	global_store_dwordx4 v[96:97], v[80:83], off offset:256
	s_cbranch_vccnz .LBB0_712
	global_store_dwordx4 v[102:103], v[80:83], off offset:256

; __device__ __forceinline__ unsigned pk2(float lo, float hi) { f32x2_t v = {lo, hi}; bf16x2_t b = __builtin_convertvector(v, bf16x2_t); return __builtin_bit_cast(unsigned, b); }
; __device__ __forceinline__ float bf_lo(unsigned w) { return __uint_as_float(w << 16); }
; __device__ __forceinline__ float bf_hi(unsigned w) { return __uint_as_float(w & 0xffff0000u); }
;     __device__ __forceinline__ void operator()(const f32x4 (&acc)[2][2][4][2], const Unit& u, int wr, int wc, int fr, int fq) const {
;     ...
;             for (int m = 0; m < 4; ++m) { const size_t off = (size_t)(row0 + ai * HALF + m * 16) * DM + col0; float sq = 0.f;
; #pragma unroll
;                 for (int bj = 0; bj < 2; ++bj) { f32x4 o[2];
;                     if (bbase) { const u32x4 w = *(const u32x4*)(bbase + off + bj * HALF);
;                         o[0] = (f32x4){bf_lo(w.x), bf_hi(w.x), bf_lo(w.y), bf_hi(w.y)} + acc[ai][bj][m][0]; o[1] = (f32x4){bf_lo(w.z), bf_hi(w.z), bf_lo(w.w), bf_hi(w.w)} + acc[ai][bj][m][1]; }
;                     else { o[0] = *(const f32x4*)(base + off + bj * HALF) + acc[ai][bj][m][0]; o[1] = *(const f32x4*)(base + off + bj * HALF + 4) + acc[ai][bj][m][1]; }
; #pragma unroll
;                     for (int n = 0; n < 2; ++n) { if (out) *(f32x4*)(out + off + bj * HALF + 4 * n) = o[n];
;                         sq += (o[n][0] * o[n][0] + o[n][1] * o[n][1]) + (o[n][2] * o[n][2] + o[n][3] * o[n][3]); }
;                     if (xb) { u32x4 w; w.x = pk2(o[0][0], o[0][1]); w.y = pk2(o[0][2], o[0][3]); w.z = pk2(o[1][0], o[1][1]); w.w = pk2(o[1][2], o[1][3]); *(u32x4*)(xb + off + bj * HALF) = w; if (xb2) *(u32x4*)(xb2 + off + bj * HALF) = w; } }
.LBB0_714:
	s_or_b64 exec, exec, s[24:25]
	v_or_b32_e32 v80, 48, v156
	v_ashrrev_i32_e32 v81, 31, v80
	v_lshlrev_b64 v[80:81], 10, v[80:81]
	v_lshl_add_u64 v[86:87], v[80:81], 0, v[154:155]
	v_lshl_add_u64 v[80:81], v[86:87], 1, s[28:29]
	s_nop 1
	v_mov_b32_e32 v82, v202
	v_mov_b32_e32 v83, v203
	v_mov_b32_e32 v84, v204
	v_mov_b32_e32 v85, v205
	v_readlane_b32 s64, v247, 39
	v_readlane_b32 s78, v247, 53
	v_readlane_b32 s79, v247, 54
	s_and_b64 vcc, exec, s[8:9]
	v_readlane_b32 s65, v247, 40
	v_lshl_add_u64 v[86:87], v[86:87], 1, s[78:79]
	v_readlane_b32 s66, v247, 41
	v_readlane_b32 s67, v247, 42
	v_readlane_b32 s68, v247, 43
	v_readlane_b32 s69, v247, 44
	v_readlane_b32 s70, v247, 45
	v_readlane_b32 s71, v247, 46
	v_readlane_b32 s72, v247, 47
	v_readlane_b32 s73, v247, 48
	v_readlane_b32 s74, v247, 49
	v_readlane_b32 s75, v247, 50
	v_readlane_b32 s76, v247, 51
	v_readlane_b32 s77, v247, 52
	v_lshlrev_b32_e32 v88, 16, v82
	v_and_b32_e32 v89, 0xffff0000, v82
	v_lshlrev_b32_e32 v82, 16, v83
	v_and_b32_e32 v83, 0xffff0000, v83
	v_lshlrev_b32_e32 v90, 16, v84
	v_and_b32_e32 v91, 0xffff0000, v84
	v_lshlrev_b32_e32 v92, 16, v85
	v_and_b32_e32 v93, 0xffff0000, v85
	v_pk_add_f32 v[82:83], v[78:79], v[82:83]
	v_pk_add_f32 v[84:85], v[76:77], v[88:89]
	v_pk_add_f32 v[76:77], v[74:75], v[92:93]
	v_pk_add_f32 v[78:79], v[72:73], v[90:91]
	v_cvt_pk_bf16_f32 v72, v84, v85
	v_cvt_pk_bf16_f32 v73, v82, v83
	v_cvt_pk_bf16_f32 v74, v78, v79
	v_cvt_pk_bf16_f32 v75, v76, v77
	global_store_dwordx4 v[80:81], v[72:75], off
	s_cbranch_vccnz .LBB0_716
	global_store_dwordx4 v[86:87], v[72:75], off
.LBB0_716:
	s_nop 1
	v_mov_b32_e32 v72, v208
	v_mov_b32_e32 v73, v209
	v_mov_b32_e32 v74, v210
	v_mov_b32_e32 v75, v211
	s_and_b64 vcc, exec, s[8:9]
	v_lshlrev_b32_e32 v88, 16, v72
	v_and_b32_e32 v89, 0xffff0000, v72
	v_lshlrev_b32_e32 v72, 16, v73
	v_and_b32_e32 v73, 0xffff0000, v73
	v_lshlrev_b32_e32 v90, 16, v74
	v_and_b32_e32 v91, 0xffff0000, v74
	v_lshlrev_b32_e32 v74, 16, v75
	v_and_b32_e32 v75, 0xffff0000, v75
	v_pk_add_f32 v[70:71], v[70:71], v[72:73]
	v_pk_add_f32 v[72:73], v[68:69], v[88:89]
	v_pk_add_f32 v[68:69], v[66:67], v[74:75]
	v_pk_add_f32 v[74:75], v[64:65], v[90:91]
	v_cvt_pk_bf16_f32 v64, v72, v73
	v_cvt_pk_bf16_f32 v65, v70, v71
	v_cvt_pk_bf16_f32 v66, v74, v75
	v_cvt_pk_bf16_f32 v67, v68, v69
	global_store_dwordx4 v[80:81], v[64:67], off offset:256
	s_cbranch_vccnz .LBB0_718
	global_store_dwordx4 v[86:87], v[64:67], off offset:256

; __device__ __forceinline__ unsigned pk2(float lo, float hi) { f32x2_t v = {lo, hi}; bf16x2_t b = __builtin_convertvector(v, bf16x2_t); return __builtin_bit_cast(unsigned, b); }
; __device__ __forceinline__ float bf_lo(unsigned w) { return __uint_as_float(w << 16); }
; __device__ __forceinline__ float bf_hi(unsigned w) { return __uint_as_float(w & 0xffff0000u); }
;     __device__ __forceinline__ void operator()(const f32x4 (&acc)[2][2][4][2], const Unit& u, int wr, int wc, int fr, int fq) const {
;     ...
;             for (int m = 0; m < 4; ++m) { const size_t off = (size_t)(row0 + ai * HALF + m * 16) * DM + col0; float sq = 0.f;
; #pragma unroll
;                 for (int bj = 0; bj < 2; ++bj) { f32x4 o[2];
;                     if (bbase) { const u32x4 w = *(const u32x4*)(bbase + off + bj * HALF);
;                         o[0] = (f32x4){bf_lo(w.x), bf_hi(w.x), bf_lo(w.y), bf_hi(w.y)} + acc[ai][bj][m][0]; o[1] = (f32x4){bf_lo(w.z), bf_hi(w.z), bf_lo(w.w), bf_hi(w.w)} + acc[ai][bj][m][1]; }
;                     else { o[0] = *(const f32x4*)(base + off + bj * HALF) + acc[ai][bj][m][0]; o[1] = *(const f32x4*)(base + off + bj * HALF + 4) + acc[ai][bj][m][1]; }
; #pragma unroll
;                     for (int n = 0; n < 2; ++n) { if (out) *(f32x4*)(out + off + bj * HALF + 4 * n) = o[n];
;                         sq += (o[n][0] * o[n][0] + o[n][1] * o[n][1]) + (o[n][2] * o[n][2] + o[n][3] * o[n][3]); }
;                     if (xb) { u32x4 w; w.x = pk2(o[0][0], o[0][1]); w.y = pk2(o[0][2], o[0][3]); w.z = pk2(o[1][0], o[1][1]); w.w = pk2(o[1][2], o[1][3]); *(u32x4*)(xb + off + bj * HALF) = w; if (xb2) *(u32x4*)(xb2 + off + bj * HALF) = w; } }
.LBB0_720:
	s_or_b64 exec, exec, s[24:25]
	s_mov_b64 s[24:25], 0x20000
	v_lshl_add_u64 v[70:71], v[152:153], 0, s[24:25]
	v_lshl_add_u64 v[64:65], v[70:71], 1, s[28:29]
	s_waitcnt vmcnt(0)
	s_nop 1
	v_mov_b32_e32 v66, v212
	v_mov_b32_e32 v67, v213
	v_mov_b32_e32 v68, v214
	v_mov_b32_e32 v69, v215
	v_readlane_b32 s64, v247, 39
	v_readlane_b32 s78, v247, 53
	v_readlane_b32 s79, v247, 54
	s_and_b64 vcc, exec, s[8:9]
	v_readlane_b32 s65, v247, 40
	v_lshl_add_u64 v[70:71], v[70:71], 1, s[78:79]
	v_readlane_b32 s66, v247, 41
	v_readlane_b32 s67, v247, 42
	v_readlane_b32 s68, v247, 43
	v_readlane_b32 s69, v247, 44
	v_readlane_b32 s70, v247, 45
	v_readlane_b32 s71, v247, 46
	v_readlane_b32 s72, v247, 47
	v_readlane_b32 s73, v247, 48
	v_readlane_b32 s74, v247, 49
	v_readlane_b32 s75, v247, 50
	v_readlane_b32 s76, v247, 51
	v_readlane_b32 s77, v247, 52
	v_lshlrev_b32_e32 v72, 16, v66
	v_and_b32_e32 v73, 0xffff0000, v66
	v_lshlrev_b32_e32 v66, 16, v67
	v_and_b32_e32 v67, 0xffff0000, v67
	v_lshlrev_b32_e32 v74, 16, v68
	v_and_b32_e32 v75, 0xffff0000, v68
	v_lshlrev_b32_e32 v76, 16, v69
	v_and_b32_e32 v77, 0xffff0000, v69
	v_pk_add_f32 v[66:67], v[62:63], v[66:67]
	v_pk_add_f32 v[68:69], v[60:61], v[72:73]
	v_pk_add_f32 v[60:61], v[58:59], v[76:77]
	v_pk_add_f32 v[62:63], v[56:57], v[74:75]
	v_cvt_pk_bf16_f32 v56, v68, v69
	v_cvt_pk_bf16_f32 v57, v66, v67
	v_cvt_pk_bf16_f32 v58, v62, v63
	v_cvt_pk_bf16_f32 v59, v60, v61
	global_store_dwordx4 v[64:65], v[56:59], off
	s_cbranch_vccnz .LBB0_722
	global_store_dwordx4 v[70:71], v[56:59], off
.LBB0_722:
	s_nop 1
	v_mov_b32_e32 v56, v216
	v_mov_b32_e32 v57, v217
	v_mov_b32_e32 v58, v218
	v_mov_b32_e32 v59, v219
	s_and_b64 vcc, exec, s[8:9]
	v_lshlrev_b32_e32 v72, 16, v56
	v_and_b32_e32 v73, 0xffff0000, v56
	v_lshlrev_b32_e32 v56, 16, v57
	v_and_b32_e32 v57, 0xffff0000, v57
	v_lshlrev_b32_e32 v74, 16, v58
	v_and_b32_e32 v75, 0xffff0000, v58
	v_lshlrev_b32_e32 v58, 16, v59
	v_and_b32_e32 v59, 0xffff0000, v59
	v_pk_add_f32 v[54:55], v[54:55], v[56:57]
	v_pk_add_f32 v[56:57], v[52:53], v[72:73]
	v_pk_add_f32 v[52:53], v[50:51], v[58:59]
	v_pk_add_f32 v[58:59], v[48:49], v[74:75]
	v_cvt_pk_bf16_f32 v48, v56, v57
	v_cvt_pk_bf16_f32 v49, v54, v55
	v_cvt_pk_bf16_f32 v50, v58, v59
	v_cvt_pk_bf16_f32 v51, v52, v53
	global_store_dwordx4 v[64:65], v[48:51], off offset:256
	s_cbranch_vccnz .LBB0_724
	global_store_dwordx4 v[70:71], v[48:51], off offset:256

; __device__ __forceinline__ unsigned pk2(float lo, float hi) { f32x2_t v = {lo, hi}; bf16x2_t b = __builtin_convertvector(v, bf16x2_t); return __builtin_bit_cast(unsigned, b); }
; __device__ __forceinline__ float bf_lo(unsigned w) { return __uint_as_float(w << 16); }
; __device__ __forceinline__ float bf_hi(unsigned w) { return __uint_as_float(w & 0xffff0000u); }
;     __device__ __forceinline__ void operator()(const f32x4 (&acc)[2][2][4][2], const Unit& u, int wr, int wc, int fr, int fq) const {
;     ...
;             for (int m = 0; m < 4; ++m) { const size_t off = (size_t)(row0 + ai * HALF + m * 16) * DM + col0; float sq = 0.f;
; #pragma unroll
;                 for (int bj = 0; bj < 2; ++bj) { f32x4 o[2];
;                     if (bbase) { const u32x4 w = *(const u32x4*)(bbase + off + bj * HALF);
;                         o[0] = (f32x4){bf_lo(w.x), bf_hi(w.x), bf_lo(w.y), bf_hi(w.y)} + acc[ai][bj][m][0]; o[1] = (f32x4){bf_lo(w.z), bf_hi(w.z), bf_lo(w.w), bf_hi(w.w)} + acc[ai][bj][m][1]; }
;                     else { o[0] = *(const f32x4*)(base + off + bj * HALF) + acc[ai][bj][m][0]; o[1] = *(const f32x4*)(base + off + bj * HALF + 4) + acc[ai][bj][m][1]; }
; #pragma unroll
;                     for (int n = 0; n < 2; ++n) { if (out) *(f32x4*)(out + off + bj * HALF + 4 * n) = o[n];
;                         sq += (o[n][0] * o[n][0] + o[n][1] * o[n][1]) + (o[n][2] * o[n][2] + o[n][3] * o[n][3]); }
;                     if (xb) { u32x4 w; w.x = pk2(o[0][0], o[0][1]); w.y = pk2(o[0][2], o[0][3]); w.z = pk2(o[1][0], o[1][1]); w.w = pk2(o[1][2], o[1][3]); *(u32x4*)(xb + off + bj * HALF) = w; if (xb2) *(u32x4*)(xb2 + off + bj * HALF) = w; } }
.LBB0_726:
	s_or_b64 exec, exec, s[24:25]
	s_mov_b64 s[24:25], 0x24000
	v_lshl_add_u64 v[54:55], v[152:153], 0, s[24:25]
	v_lshl_add_u64 v[48:49], v[54:55], 1, s[28:29]
	s_nop 1
	v_mov_b32_e32 v50, v220
	v_mov_b32_e32 v51, v221
	v_mov_b32_e32 v52, v222
	v_mov_b32_e32 v53, v223
	v_readlane_b32 s64, v247, 39
	v_readlane_b32 s78, v247, 53
	v_readlane_b32 s79, v247, 54
	s_and_b64 vcc, exec, s[8:9]
	v_readlane_b32 s65, v247, 40
	v_lshl_add_u64 v[54:55], v[54:55], 1, s[78:79]
	v_readlane_b32 s66, v247, 41
	v_readlane_b32 s67, v247, 42
	v_readlane_b32 s68, v247, 43
	v_readlane_b32 s69, v247, 44
	v_readlane_b32 s70, v247, 45
	v_readlane_b32 s71, v247, 46
	v_readlane_b32 s72, v247, 47
	v_readlane_b32 s73, v247, 48
	v_readlane_b32 s74, v247, 49
	v_readlane_b32 s75, v247, 50
	v_readlane_b32 s76, v247, 51
	v_readlane_b32 s77, v247, 52
	v_lshlrev_b32_e32 v56, 16, v50
	v_and_b32_e32 v57, 0xffff0000, v50
	v_lshlrev_b32_e32 v50, 16, v51
	v_and_b32_e32 v51, 0xffff0000, v51
	v_lshlrev_b32_e32 v58, 16, v52
	v_and_b32_e32 v59, 0xffff0000, v52
	v_lshlrev_b32_e32 v60, 16, v53
	v_and_b32_e32 v61, 0xffff0000, v53
	v_pk_add_f32 v[50:51], v[46:47], v[50:51]
	v_pk_add_f32 v[52:53], v[44:45], v[56:57]
	v_pk_add_f32 v[44:45], v[42:43], v[60:61]
	v_pk_add_f32 v[46:47], v[40:41], v[58:59]
	v_cvt_pk_bf16_f32 v40, v52, v53
	v_cvt_pk_bf16_f32 v41, v50, v51
	v_cvt_pk_bf16_f32 v42, v46, v47
	v_cvt_pk_bf16_f32 v43, v44, v45
	global_store_dwordx4 v[48:49], v[40:43], off
	s_cbranch_vccnz .LBB0_728
	global_store_dwordx4 v[54:55], v[40:43], off
.LBB0_728:
	s_nop 1
	v_mov_b32_e32 v40, v224
	v_mov_b32_e32 v41, v225
	v_mov_b32_e32 v42, v226
	v_mov_b32_e32 v43, v227
	s_and_b64 vcc, exec, s[8:9]
	v_lshlrev_b32_e32 v56, 16, v40
	v_and_b32_e32 v57, 0xffff0000, v40
	v_lshlrev_b32_e32 v40, 16, v41
	v_and_b32_e32 v41, 0xffff0000, v41
	v_lshlrev_b32_e32 v58, 16, v42
	v_and_b32_e32 v59, 0xffff0000, v42
	v_lshlrev_b32_e32 v42, 16, v43
	v_and_b32_e32 v43, 0xffff0000, v43
	v_pk_add_f32 v[38:39], v[38:39], v[40:41]
	v_pk_add_f32 v[40:41], v[36:37], v[56:57]
	v_pk_add_f32 v[36:37], v[34:35], v[42:43]
	v_pk_add_f32 v[42:43], v[32:33], v[58:59]
	v_cvt_pk_bf16_f32 v32, v40, v41
	v_cvt_pk_bf16_f32 v33, v38, v39
	v_cvt_pk_bf16_f32 v34, v42, v43
	v_cvt_pk_bf16_f32 v35, v36, v37
	global_store_dwordx4 v[48:49], v[32:35], off offset:256
	s_cbranch_vccnz .LBB0_730
	global_store_dwordx4 v[54:55], v[32:35], off offset:256

; __device__ __forceinline__ unsigned pk2(float lo, float hi) { f32x2_t v = {lo, hi}; bf16x2_t b = __builtin_convertvector(v, bf16x2_t); return __builtin_bit_cast(unsigned, b); }
; __device__ __forceinline__ float bf_lo(unsigned w) { return __uint_as_float(w << 16); }
; __device__ __forceinline__ float bf_hi(unsigned w) { return __uint_as_float(w & 0xffff0000u); }
;     __device__ __forceinline__ void operator()(const f32x4 (&acc)[2][2][4][2], const Unit& u, int wr, int wc, int fr, int fq) const {
;     ...
;             for (int m = 0; m < 4; ++m) { const size_t off = (size_t)(row0 + ai * HALF + m * 16) * DM + col0; float sq = 0.f;
; #pragma unroll
;                 for (int bj = 0; bj < 2; ++bj) { f32x4 o[2];
;                     if (bbase) { const u32x4 w = *(const u32x4*)(bbase + off + bj * HALF);
;                         o[0] = (f32x4){bf_lo(w.x), bf_hi(w.x), bf_lo(w.y), bf_hi(w.y)} + acc[ai][bj][m][0]; o[1] = (f32x4){bf_lo(w.z), bf_hi(w.z), bf_lo(w.w), bf_hi(w.w)} + acc[ai][bj][m][1]; }
;                     else { o[0] = *(const f32x4*)(base + off + bj * HALF) + acc[ai][bj][m][0]; o[1] = *(const f32x4*)(base + off + bj * HALF + 4) + acc[ai][bj][m][1]; }
; #pragma unroll
;                     for (int n = 0; n < 2; ++n) { if (out) *(f32x4*)(out + off + bj * HALF + 4 * n) = o[n];
;                         sq += (o[n][0] * o[n][0] + o[n][1] * o[n][1]) + (o[n][2] * o[n][2] + o[n][3] * o[n][3]); }
;                     if (xb) { u32x4 w; w.x = pk2(o[0][0], o[0][1]); w.y = pk2(o[0][2], o[0][3]); w.z = pk2(o[1][0], o[1][1]); w.w = pk2(o[1][2], o[1][3]); *(u32x4*)(xb + off + bj * HALF) = w; if (xb2) *(u32x4*)(xb2 + off + bj * HALF) = w; } }
.LBB0_732:
	s_or_b64 exec, exec, s[24:25]
	s_mov_b64 s[24:25], 0x28000
	v_lshl_add_u64 v[38:39], v[152:153], 0, s[24:25]
	v_lshl_add_u64 v[32:33], v[38:39], 1, s[28:29]
	s_nop 1
	v_mov_b32_e32 v34, v174
	v_mov_b32_e32 v35, v175
	v_mov_b32_e32 v36, v176
	v_mov_b32_e32 v37, v177
	v_readlane_b32 s64, v247, 39
	v_readlane_b32 s78, v247, 53
	v_readlane_b32 s79, v247, 54
	s_and_b64 vcc, exec, s[8:9]
	v_readlane_b32 s65, v247, 40
	v_lshl_add_u64 v[38:39], v[38:39], 1, s[78:79]
	v_readlane_b32 s66, v247, 41
	v_readlane_b32 s67, v247, 42
	v_readlane_b32 s68, v247, 43
	v_readlane_b32 s69, v247, 44
	v_readlane_b32 s70, v247, 45
	v_readlane_b32 s71, v247, 46
	v_readlane_b32 s72, v247, 47
	v_readlane_b32 s73, v247, 48
	v_readlane_b32 s74, v247, 49
	v_readlane_b32 s75, v247, 50
	v_readlane_b32 s76, v247, 51
	v_readlane_b32 s77, v247, 52
	v_lshlrev_b32_e32 v40, 16, v34
	v_and_b32_e32 v41, 0xffff0000, v34
	v_lshlrev_b32_e32 v34, 16, v35
	v_and_b32_e32 v35, 0xffff0000, v35
	v_lshlrev_b32_e32 v42, 16, v36
	v_and_b32_e32 v43, 0xffff0000, v36
	v_lshlrev_b32_e32 v44, 16, v37
	v_and_b32_e32 v45, 0xffff0000, v37
	v_pk_add_f32 v[34:35], v[30:31], v[34:35]
	v_pk_add_f32 v[36:37], v[28:29], v[40:41]
	v_pk_add_f32 v[28:29], v[26:27], v[44:45]
	v_pk_add_f32 v[30:31], v[24:25], v[42:43]
	v_cvt_pk_bf16_f32 v24, v36, v37
	v_cvt_pk_bf16_f32 v25, v34, v35
	v_cvt_pk_bf16_f32 v26, v30, v31
	v_cvt_pk_bf16_f32 v27, v28, v29
	global_store_dwordx4 v[32:33], v[24:27], off
	s_cbranch_vccnz .LBB0_734
	global_store_dwordx4 v[38:39], v[24:27], off
.LBB0_734:
	s_nop 1
	v_mov_b32_e32 v24, v178
	v_mov_b32_e32 v25, v179
	v_mov_b32_e32 v26, v180
	v_mov_b32_e32 v27, v181
	s_and_b64 vcc, exec, s[8:9]
	v_lshlrev_b32_e32 v40, 16, v24
	v_and_b32_e32 v41, 0xffff0000, v24
	v_lshlrev_b32_e32 v24, 16, v25
	v_and_b32_e32 v25, 0xffff0000, v25
	v_lshlrev_b32_e32 v42, 16, v26
	v_and_b32_e32 v43, 0xffff0000, v26
	v_lshlrev_b32_e32 v26, 16, v27
	v_and_b32_e32 v27, 0xffff0000, v27
	v_pk_add_f32 v[22:23], v[22:23], v[24:25]
	v_pk_add_f32 v[24:25], v[20:21], v[40:41]
	v_pk_add_f32 v[20:21], v[18:19], v[26:27]
	v_pk_add_f32 v[26:27], v[16:17], v[42:43]
	v_cvt_pk_bf16_f32 v16, v24, v25
	v_cvt_pk_bf16_f32 v17, v22, v23
	v_cvt_pk_bf16_f32 v18, v26, v27
	v_cvt_pk_bf16_f32 v19, v20, v21
	global_store_dwordx4 v[32:33], v[16:19], off offset:256
	s_cbranch_vccnz .LBB0_736
	global_store_dwordx4 v[38:39], v[16:19], off offset:256

; __device__ __forceinline__ unsigned pk2(float lo, float hi) { f32x2_t v = {lo, hi}; bf16x2_t b = __builtin_convertvector(v, bf16x2_t); return __builtin_bit_cast(unsigned, b); }
; __device__ __forceinline__ float bf_lo(unsigned w) { return __uint_as_float(w << 16); }
; __device__ __forceinline__ float bf_hi(unsigned w) { return __uint_as_float(w & 0xffff0000u); }
;     __device__ __forceinline__ void operator()(const f32x4 (&acc)[2][2][4][2], const Unit& u, int wr, int wc, int fr, int fq) const {
;     ...
;             for (int m = 0; m < 4; ++m) { const size_t off = (size_t)(row0 + ai * HALF + m * 16) * DM + col0; float sq = 0.f;
; #pragma unroll
;                 for (int bj = 0; bj < 2; ++bj) { f32x4 o[2];
;                     if (bbase) { const u32x4 w = *(const u32x4*)(bbase + off + bj * HALF);
;                         o[0] = (f32x4){bf_lo(w.x), bf_hi(w.x), bf_lo(w.y), bf_hi(w.y)} + acc[ai][bj][m][0]; o[1] = (f32x4){bf_lo(w.z), bf_hi(w.z), bf_lo(w.w), bf_hi(w.w)} + acc[ai][bj][m][1]; }
;                     else { o[0] = *(const f32x4*)(base + off + bj * HALF) + acc[ai][bj][m][0]; o[1] = *(const f32x4*)(base + off + bj * HALF + 4) + acc[ai][bj][m][1]; }
; #pragma unroll
;                     for (int n = 0; n < 2; ++n) { if (out) *(f32x4*)(out + off + bj * HALF + 4 * n) = o[n];
;                         sq += (o[n][0] * o[n][0] + o[n][1] * o[n][1]) + (o[n][2] * o[n][2] + o[n][3] * o[n][3]); }
;                     if (xb) { u32x4 w; w.x = pk2(o[0][0], o[0][1]); w.y = pk2(o[0][2], o[0][3]); w.z = pk2(o[1][0], o[1][1]); w.w = pk2(o[1][2], o[1][3]); *(u32x4*)(xb + off + bj * HALF) = w; if (xb2) *(u32x4*)(xb2 + off + bj * HALF) = w; } }
.LBB0_738:
	s_or_b64 exec, exec, s[24:25]
	s_mov_b64 s[24:25], 0x2c000
	v_lshl_add_u64 v[22:23], v[152:153], 0, s[24:25]
	v_lshl_add_u64 v[16:17], v[22:23], 1, s[28:29]
	s_nop 1
	v_mov_b32_e32 v18, v182
	v_mov_b32_e32 v19, v183
	v_mov_b32_e32 v20, v184
	v_mov_b32_e32 v21, v185
	v_readlane_b32 s64, v247, 39
	v_readlane_b32 s78, v247, 53
	v_readlane_b32 s79, v247, 54
	s_and_b64 vcc, exec, s[8:9]
	v_readlane_b32 s65, v247, 40
	v_lshl_add_u64 v[22:23], v[22:23], 1, s[78:79]
	v_readlane_b32 s66, v247, 41
	v_readlane_b32 s67, v247, 42
	v_readlane_b32 s68, v247, 43
	v_readlane_b32 s69, v247, 44
	v_readlane_b32 s70, v247, 45
	v_readlane_b32 s71, v247, 46
	v_readlane_b32 s72, v247, 47
	v_readlane_b32 s73, v247, 48
	v_readlane_b32 s74, v247, 49
	v_readlane_b32 s75, v247, 50
	v_readlane_b32 s76, v247, 51
	v_readlane_b32 s77, v247, 52
	v_lshlrev_b32_e32 v24, 16, v18
	v_and_b32_e32 v25, 0xffff0000, v18
	v_lshlrev_b32_e32 v18, 16, v19
	v_and_b32_e32 v19, 0xffff0000, v19
	v_lshlrev_b32_e32 v26, 16, v20
	v_and_b32_e32 v27, 0xffff0000, v20
	v_lshlrev_b32_e32 v28, 16, v21
	v_and_b32_e32 v29, 0xffff0000, v21
	v_pk_add_f32 v[18:19], v[14:15], v[18:19]
	v_pk_add_f32 v[20:21], v[12:13], v[24:25]
	v_pk_add_f32 v[12:13], v[10:11], v[28:29]
	v_pk_add_f32 v[14:15], v[8:9], v[26:27]
	v_cvt_pk_bf16_f32 v8, v20, v21
	v_cvt_pk_bf16_f32 v9, v18, v19
	v_cvt_pk_bf16_f32 v10, v14, v15
	v_cvt_pk_bf16_f32 v11, v12, v13
	global_store_dwordx4 v[16:17], v[8:11], off
	s_cbranch_vccnz .LBB0_740
	global_store_dwordx4 v[22:23], v[8:11], off
.LBB0_740:
	s_nop 1
	v_mov_b32_e32 v8, v186
	v_mov_b32_e32 v9, v187
	v_mov_b32_e32 v10, v188
	v_mov_b32_e32 v11, v189
	s_and_b64 vcc, exec, s[8:9]
	v_lshlrev_b32_e32 v24, 16, v8
	v_and_b32_e32 v25, 0xffff0000, v8
	v_lshlrev_b32_e32 v8, 16, v9
	v_and_b32_e32 v9, 0xffff0000, v9
	v_lshlrev_b32_e32 v26, 16, v10
	v_and_b32_e32 v27, 0xffff0000, v10
	v_lshlrev_b32_e32 v10, 16, v11
	v_and_b32_e32 v11, 0xffff0000, v11
	v_pk_add_f32 v[6:7], v[6:7], v[8:9]
	v_pk_add_f32 v[8:9], v[4:5], v[24:25]
	v_pk_add_f32 v[4:5], v[2:3], v[10:11]
	v_pk_add_f32 v[10:11], v[0:1], v[26:27]
	v_cvt_pk_bf16_f32 v0, v8, v9
	v_cvt_pk_bf16_f32 v1, v6, v7
	v_cvt_pk_bf16_f32 v2, v10, v11
	v_cvt_pk_bf16_f32 v3, v4, v5
	global_store_dwordx4 v[16:17], v[0:3], off offset:256
	s_cbranch_vccnz .LBB0_742
	global_store_dwordx4 v[22:23], v[0:3], off offset:256

; __device__ __forceinline__ unsigned pk2(float lo, float hi) { f32x2_t v = {lo, hi}; bf16x2_t b = __builtin_convertvector(v, bf16x2_t); return __builtin_bit_cast(unsigned, b); }
; __device__ __forceinline__ float bf_lo(unsigned w) { return __uint_as_float(w << 16); }
; __device__ __forceinline__ float bf_hi(unsigned w) { return __uint_as_float(w & 0xffff0000u); }
;     __device__ __forceinline__ void operator()(const f32x4 (&acc)[2][2][4][2], const Unit& u, int wr, int wc, int fr, int fq) const {
;     ...
;             for (int m = 0; m < 4; ++m) { const size_t off = (size_t)(row0 + ai * HALF + m * 16) * DM + col0; float sq = 0.f;
; #pragma unroll
;                 for (int bj = 0; bj < 2; ++bj) { f32x4 o[2];
;                     if (bbase) { const u32x4 w = *(const u32x4*)(bbase + off + bj * HALF);
;                         o[0] = (f32x4){bf_lo(w.x), bf_hi(w.x), bf_lo(w.y), bf_hi(w.y)} + acc[ai][bj][m][0]; o[1] = (f32x4){bf_lo(w.z), bf_hi(w.z), bf_lo(w.w), bf_hi(w.w)} + acc[ai][bj][m][1]; }
;                     else { o[0] = *(const f32x4*)(base + off + bj * HALF) + acc[ai][bj][m][0]; o[1] = *(const f32x4*)(base + off + bj * HALF + 4) + acc[ai][bj][m][1]; }
; #pragma unroll
;                     for (int n = 0; n < 2; ++n) { if (out) *(f32x4*)(out + off + bj * HALF + 4 * n) = o[n];
;                         sq += (o[n][0] * o[n][0] + o[n][1] * o[n][1]) + (o[n][2] * o[n][2] + o[n][3] * o[n][3]); }
;                     if (xb) { u32x4 w; w.x = pk2(o[0][0], o[0][1]); w.y = pk2(o[0][2], o[0][3]); w.z = pk2(o[1][0], o[1][1]); w.w = pk2(o[1][2], o[1][3]); *(u32x4*)(xb + off + bj * HALF) = w; if (xb2) *(u32x4*)(xb2 + off + bj * HALF) = w; } }
.LBB0_1206:
	v_lshl_add_u32 v144, s58, 8, v154
	v_lshl_or_b32 v148, s38, 8, v156
	v_ashrrev_i32_e32 v145, 31, v144
	v_ashrrev_i32_e32 v149, 31, v148
	v_lshlrev_b64 v[146:147], 10, v[144:145]
	v_lshl_add_u64 v[146:147], v[146:147], 0, v[148:149]
	v_lshl_add_u64 v[152:153], v[146:147], 1, s[66:67]
	v_mov_b32_e32 v204, v152
	v_mov_b32_e32 v205, v153
	global_load_dwordx4 v[164:167], v[204:205], off
	global_load_dwordx4 v[168:171], v[204:205], off offset:256
	s_mov_b32 s98, 0x8000
	s_mov_b32 s99, 0
	v_lshl_add_u64 v[248:249], v[204:205], 0, s[98:99]
	global_load_dwordx4 v[172:175], v[248:249], off
	global_load_dwordx4 v[176:179], v[248:249], off offset:256
	s_mov_b32 s98, 0x10000
	s_mov_b32 s99, 0
	v_lshl_add_u64 v[248:249], v[204:205], 0, s[98:99]
	global_load_dwordx4 v[180:183], v[248:249], off
	global_load_dwordx4 v[184:187], v[248:249], off offset:256
	s_mov_b32 s98, 0x18000
	s_mov_b32 s99, 0
	v_lshl_add_u64 v[248:249], v[204:205], 0, s[98:99]
	global_load_dwordx4 v[188:191], v[248:249], off
	global_load_dwordx4 v[192:195], v[248:249], off offset:256
	s_waitcnt vmcnt(0)
	s_nop 1
	v_mov_b32_e32 v158, v164
	v_mov_b32_e32 v159, v165
	v_mov_b32_e32 v160, v166
	v_mov_b32_e32 v161, v167
	v_cndmask_b32_e64 v150, 0, 1, s[20:21]
	v_cmp_ne_u32_e64 s[6:7], 1, v150
	s_andn2_b64 vcc, exec, s[20:21]
	v_lshlrev_b32_e32 v150, 16, v158
	v_and_b32_e32 v151, 0xffff0000, v158
	v_lshlrev_b32_e32 v158, 16, v159
	v_and_b32_e32 v159, 0xffff0000, v159
	v_lshlrev_b32_e32 v162, 16, v160
	v_and_b32_e32 v163, 0xffff0000, v160
	v_lshlrev_b32_e32 v160, 16, v161
	v_and_b32_e32 v161, 0xffff0000, v161
	v_pk_add_f32 v[126:127], v[126:127], v[158:159]
	v_pk_add_f32 v[124:125], v[124:125], v[150:151]
	v_pk_add_f32 v[122:123], v[122:123], v[160:161]
	v_pk_add_f32 v[120:121], v[120:121], v[162:163]
	v_lshl_add_u64 v[150:151], v[146:147], 1, s[8:9]
	s_cbranch_vccnz .LBB0_1208
	v_cvt_pk_bf16_f32 v158, v124, v125
	v_cvt_pk_bf16_f32 v159, v126, v127
	v_cvt_pk_bf16_f32 v160, v120, v121
	v_cvt_pk_bf16_f32 v161, v122, v123
	global_store_dwordx4 v[150:151], v[158:161], off
.LBB0_1208:
	s_nop 1
	v_mov_b32_e32 v158, v168
	v_mov_b32_e32 v159, v169
	v_mov_b32_e32 v160, v170
	v_mov_b32_e32 v161, v171
	s_and_b64 vcc, exec, s[6:7]
	v_lshlrev_b32_e32 v152, 16, v158
	v_and_b32_e32 v153, 0xffff0000, v158
	v_lshlrev_b32_e32 v158, 16, v159
	v_and_b32_e32 v159, 0xffff0000, v159
	v_lshlrev_b32_e32 v162, 16, v160
	v_and_b32_e32 v163, 0xffff0000, v160
	v_lshlrev_b32_e32 v160, 16, v161
	v_and_b32_e32 v161, 0xffff0000, v161
	v_pk_add_f32 v[118:119], v[118:119], v[158:159]
	v_pk_add_f32 v[116:117], v[116:117], v[152:153]
	v_pk_add_f32 v[114:115], v[114:115], v[160:161]
	v_pk_add_f32 v[112:113], v[112:113], v[162:163]
	s_cbranch_vccnz .LBB0_1210
	v_cvt_pk_bf16_f32 v158, v116, v117
	v_cvt_pk_bf16_f32 v159, v118, v119
	v_cvt_pk_bf16_f32 v160, v112, v113
	v_cvt_pk_bf16_f32 v161, v114, v115
	global_store_dwordx4 v[150:151], v[158:161], off offset:256

; __device__ __forceinline__ unsigned pk2(float lo, float hi) { f32x2_t v = {lo, hi}; bf16x2_t b = __builtin_convertvector(v, bf16x2_t); return __builtin_bit_cast(unsigned, b); }
; __device__ __forceinline__ float bf_lo(unsigned w) { return __uint_as_float(w << 16); }
; __device__ __forceinline__ float bf_hi(unsigned w) { return __uint_as_float(w & 0xffff0000u); }
;     __device__ __forceinline__ void operator()(const f32x4 (&acc)[2][2][4][2], const Unit& u, int wr, int wc, int fr, int fq) const {
;     ...
;             for (int m = 0; m < 4; ++m) { const size_t off = (size_t)(row0 + ai * HALF + m * 16) * DM + col0; float sq = 0.f;
; #pragma unroll
;                 for (int bj = 0; bj < 2; ++bj) { f32x4 o[2];
;                     if (bbase) { const u32x4 w = *(const u32x4*)(bbase + off + bj * HALF);
;                         o[0] = (f32x4){bf_lo(w.x), bf_hi(w.x), bf_lo(w.y), bf_hi(w.y)} + acc[ai][bj][m][0]; o[1] = (f32x4){bf_lo(w.z), bf_hi(w.z), bf_lo(w.w), bf_hi(w.w)} + acc[ai][bj][m][1]; }
;                     else { o[0] = *(const f32x4*)(base + off + bj * HALF) + acc[ai][bj][m][0]; o[1] = *(const f32x4*)(base + off + bj * HALF + 4) + acc[ai][bj][m][1]; }
; #pragma unroll
;                     for (int n = 0; n < 2; ++n) { if (out) *(f32x4*)(out + off + bj * HALF + 4 * n) = o[n];
;                         sq += (o[n][0] * o[n][0] + o[n][1] * o[n][1]) + (o[n][2] * o[n][2] + o[n][3] * o[n][3]); }
;                     if (xb) { u32x4 w; w.x = pk2(o[0][0], o[0][1]); w.y = pk2(o[0][2], o[0][3]); w.z = pk2(o[1][0], o[1][1]); w.w = pk2(o[1][2], o[1][3]); *(u32x4*)(xb + off + bj * HALF) = w; if (xb2) *(u32x4*)(xb2 + off + bj * HALF) = w; } }
.LBB0_1214:
	v_or_b32_e32 v112, 16, v144
	v_ashrrev_i32_e32 v113, 31, v112
	v_lshlrev_b64 v[112:113], 10, v[112:113]
	v_lshl_add_u64 v[112:113], v[112:113], 0, v[148:149]
	v_lshl_add_u64 v[114:115], v[112:113], 1, s[66:67]
	s_nop 1
	v_mov_b32_e32 v116, v172
	v_mov_b32_e32 v117, v173
	v_mov_b32_e32 v118, v174
	v_mov_b32_e32 v119, v175
	s_and_b64 vcc, exec, s[6:7]
	v_lshl_add_u64 v[112:113], v[112:113], 1, s[8:9]
	v_lshlrev_b32_e32 v120, 16, v116
	v_and_b32_e32 v121, 0xffff0000, v116
	v_lshlrev_b32_e32 v116, 16, v117
	v_and_b32_e32 v117, 0xffff0000, v117
	v_lshlrev_b32_e32 v122, 16, v118
	v_and_b32_e32 v123, 0xffff0000, v118
	v_lshlrev_b32_e32 v118, 16, v119
	v_and_b32_e32 v119, 0xffff0000, v119
	v_pk_add_f32 v[110:111], v[110:111], v[116:117]
	v_pk_add_f32 v[108:109], v[108:109], v[120:121]
	v_pk_add_f32 v[106:107], v[106:107], v[118:119]
	v_pk_add_f32 v[104:105], v[104:105], v[122:123]
	s_cbranch_vccnz .LBB0_1216
	v_cvt_pk_bf16_f32 v116, v108, v109
	v_cvt_pk_bf16_f32 v117, v110, v111
	v_cvt_pk_bf16_f32 v118, v104, v105
	v_cvt_pk_bf16_f32 v119, v106, v107
	global_store_dwordx4 v[112:113], v[116:119], off
.LBB0_1216:
	s_nop 1
	v_mov_b32_e32 v114, v176
	v_mov_b32_e32 v115, v177
	v_mov_b32_e32 v116, v178
	v_mov_b32_e32 v117, v179
	s_mov_b32 s98, 0x40000
	s_mov_b32 s99, 0
	v_lshl_add_u64 v[248:249], v[204:205], 0, s[98:99]
	global_load_dwordx4 v[196:199], v[248:249], off
	global_load_dwordx4 v[200:203], v[248:249], off offset:256
	s_mov_b32 s98, 0x48000
	s_mov_b32 s99, 0
	v_lshl_add_u64 v[248:249], v[204:205], 0, s[98:99]
	global_load_dwordx4 v[208:211], v[248:249], off
	global_load_dwordx4 v[212:215], v[248:249], off offset:256
	s_mov_b32 s98, 0x50000
	s_mov_b32 s99, 0
	v_lshl_add_u64 v[248:249], v[204:205], 0, s[98:99]
	global_load_dwordx4 v[164:167], v[248:249], off
	global_load_dwordx4 v[168:171], v[248:249], off offset:256
	s_mov_b32 s98, 0x58000
	s_mov_b32 s99, 0
	v_lshl_add_u64 v[248:249], v[204:205], 0, s[98:99]
	global_load_dwordx4 v[172:175], v[248:249], off
	global_load_dwordx4 v[176:179], v[248:249], off offset:256
	s_and_b64 vcc, exec, s[6:7]
	v_lshlrev_b32_e32 v118, 16, v114
	v_and_b32_e32 v119, 0xffff0000, v114
	v_lshlrev_b32_e32 v114, 16, v115
	v_and_b32_e32 v115, 0xffff0000, v115
	v_lshlrev_b32_e32 v120, 16, v116
	v_and_b32_e32 v121, 0xffff0000, v116
	v_lshlrev_b32_e32 v116, 16, v117
	v_and_b32_e32 v117, 0xffff0000, v117
	v_pk_add_f32 v[102:103], v[102:103], v[114:115]
	v_pk_add_f32 v[100:101], v[100:101], v[118:119]
	v_pk_add_f32 v[98:99], v[98:99], v[116:117]
	v_pk_add_f32 v[96:97], v[96:97], v[120:121]
	s_cbranch_vccnz .LBB0_1218
	v_cvt_pk_bf16_f32 v114, v100, v101
	v_cvt_pk_bf16_f32 v115, v102, v103
	v_cvt_pk_bf16_f32 v116, v96, v97
	v_cvt_pk_bf16_f32 v117, v98, v99
	global_store_dwordx4 v[112:113], v[114:117], off offset:256

; __device__ __forceinline__ unsigned pk2(float lo, float hi) { f32x2_t v = {lo, hi}; bf16x2_t b = __builtin_convertvector(v, bf16x2_t); return __builtin_bit_cast(unsigned, b); }
; __device__ __forceinline__ float bf_lo(unsigned w) { return __uint_as_float(w << 16); }
; __device__ __forceinline__ float bf_hi(unsigned w) { return __uint_as_float(w & 0xffff0000u); }
;     __device__ __forceinline__ void operator()(const f32x4 (&acc)[2][2][4][2], const Unit& u, int wr, int wc, int fr, int fq) const {
;     ...
;             for (int m = 0; m < 4; ++m) { const size_t off = (size_t)(row0 + ai * HALF + m * 16) * DM + col0; float sq = 0.f;
; #pragma unroll
;                 for (int bj = 0; bj < 2; ++bj) { f32x4 o[2];
;                     if (bbase) { const u32x4 w = *(const u32x4*)(bbase + off + bj * HALF);
;                         o[0] = (f32x4){bf_lo(w.x), bf_hi(w.x), bf_lo(w.y), bf_hi(w.y)} + acc[ai][bj][m][0]; o[1] = (f32x4){bf_lo(w.z), bf_hi(w.z), bf_lo(w.w), bf_hi(w.w)} + acc[ai][bj][m][1]; }
;                     else { o[0] = *(const f32x4*)(base + off + bj * HALF) + acc[ai][bj][m][0]; o[1] = *(const f32x4*)(base + off + bj * HALF + 4) + acc[ai][bj][m][1]; }
; #pragma unroll
;                     for (int n = 0; n < 2; ++n) { if (out) *(f32x4*)(out + off + bj * HALF + 4 * n) = o[n];
;                         sq += (o[n][0] * o[n][0] + o[n][1] * o[n][1]) + (o[n][2] * o[n][2] + o[n][3] * o[n][3]); }
;                     if (xb) { u32x4 w; w.x = pk2(o[0][0], o[0][1]); w.y = pk2(o[0][2], o[0][3]); w.z = pk2(o[1][0], o[1][1]); w.w = pk2(o[1][2], o[1][3]); *(u32x4*)(xb + off + bj * HALF) = w; if (xb2) *(u32x4*)(xb2 + off + bj * HALF) = w; } }
.LBB0_1222:
	v_or_b32_e32 v96, 32, v144
	v_ashrrev_i32_e32 v97, 31, v96
	v_lshlrev_b64 v[96:97], 10, v[96:97]
	v_lshl_add_u64 v[96:97], v[96:97], 0, v[148:149]
	v_lshl_add_u64 v[98:99], v[96:97], 1, s[66:67]
	s_nop 1
	v_mov_b32_e32 v100, v180
	v_mov_b32_e32 v101, v181
	v_mov_b32_e32 v102, v182
	v_mov_b32_e32 v103, v183
	s_and_b64 vcc, exec, s[6:7]
	v_lshl_add_u64 v[96:97], v[96:97], 1, s[8:9]
	v_lshlrev_b32_e32 v104, 16, v100
	v_and_b32_e32 v105, 0xffff0000, v100
	v_lshlrev_b32_e32 v100, 16, v101
	v_and_b32_e32 v101, 0xffff0000, v101
	v_lshlrev_b32_e32 v106, 16, v102
	v_and_b32_e32 v107, 0xffff0000, v102
	v_lshlrev_b32_e32 v102, 16, v103
	v_and_b32_e32 v103, 0xffff0000, v103
	v_pk_add_f32 v[94:95], v[94:95], v[100:101]
	v_pk_add_f32 v[92:93], v[92:93], v[104:105]
	v_pk_add_f32 v[90:91], v[90:91], v[102:103]
	v_pk_add_f32 v[88:89], v[88:89], v[106:107]
	s_cbranch_vccnz .LBB0_1224
	v_cvt_pk_bf16_f32 v100, v92, v93
	v_cvt_pk_bf16_f32 v101, v94, v95
	v_cvt_pk_bf16_f32 v102, v88, v89
	v_cvt_pk_bf16_f32 v103, v90, v91
	global_store_dwordx4 v[96:97], v[100:103], off
.LBB0_1224:
	s_nop 1
	v_mov_b32_e32 v98, v184
	v_mov_b32_e32 v99, v185
	v_mov_b32_e32 v100, v186
	v_mov_b32_e32 v101, v187
	s_and_b64 vcc, exec, s[6:7]
	v_lshlrev_b32_e32 v102, 16, v98
	v_and_b32_e32 v103, 0xffff0000, v98
	v_lshlrev_b32_e32 v98, 16, v99
	v_and_b32_e32 v99, 0xffff0000, v99
	v_lshlrev_b32_e32 v104, 16, v100
	v_and_b32_e32 v105, 0xffff0000, v100
	v_lshlrev_b32_e32 v100, 16, v101
	v_and_b32_e32 v101, 0xffff0000, v101
	v_pk_add_f32 v[86:87], v[86:87], v[98:99]
	v_pk_add_f32 v[84:85], v[84:85], v[102:103]
	v_pk_add_f32 v[82:83], v[82:83], v[100:101]
	v_pk_add_f32 v[80:81], v[80:81], v[104:105]
	s_cbranch_vccnz .LBB0_1226
	v_cvt_pk_bf16_f32 v98, v84, v85
	v_cvt_pk_bf16_f32 v99, v86, v87
	v_cvt_pk_bf16_f32 v100, v80, v81
	v_cvt_pk_bf16_f32 v101, v82, v83
	global_store_dwordx4 v[96:97], v[98:101], off offset:256

; __device__ __forceinline__ unsigned pk2(float lo, float hi) { f32x2_t v = {lo, hi}; bf16x2_t b = __builtin_convertvector(v, bf16x2_t); return __builtin_bit_cast(unsigned, b); }
; __device__ __forceinline__ float bf_lo(unsigned w) { return __uint_as_float(w << 16); }
; __device__ __forceinline__ float bf_hi(unsigned w) { return __uint_as_float(w & 0xffff0000u); }
;     __device__ __forceinline__ void operator()(const f32x4 (&acc)[2][2][4][2], const Unit& u, int wr, int wc, int fr, int fq) const {
;     ...
;             for (int m = 0; m < 4; ++m) { const size_t off = (size_t)(row0 + ai * HALF + m * 16) * DM + col0; float sq = 0.f;
; #pragma unroll
;                 for (int bj = 0; bj < 2; ++bj) { f32x4 o[2];
;                     if (bbase) { const u32x4 w = *(const u32x4*)(bbase + off + bj * HALF);
;                         o[0] = (f32x4){bf_lo(w.x), bf_hi(w.x), bf_lo(w.y), bf_hi(w.y)} + acc[ai][bj][m][0]; o[1] = (f32x4){bf_lo(w.z), bf_hi(w.z), bf_lo(w.w), bf_hi(w.w)} + acc[ai][bj][m][1]; }
;                     else { o[0] = *(const f32x4*)(base + off + bj * HALF) + acc[ai][bj][m][0]; o[1] = *(const f32x4*)(base + off + bj * HALF + 4) + acc[ai][bj][m][1]; }
; #pragma unroll
;                     for (int n = 0; n < 2; ++n) { if (out) *(f32x4*)(out + off + bj * HALF + 4 * n) = o[n];
;                         sq += (o[n][0] * o[n][0] + o[n][1] * o[n][1]) + (o[n][2] * o[n][2] + o[n][3] * o[n][3]); }
;                     if (xb) { u32x4 w; w.x = pk2(o[0][0], o[0][1]); w.y = pk2(o[0][2], o[0][3]); w.z = pk2(o[1][0], o[1][1]); w.w = pk2(o[1][2], o[1][3]); *(u32x4*)(xb + off + bj * HALF) = w; if (xb2) *(u32x4*)(xb2 + off + bj * HALF) = w; } }
.LBB0_1230:
	v_or_b32_e32 v80, 48, v144
	v_ashrrev_i32_e32 v81, 31, v80
	v_lshlrev_b64 v[80:81], 10, v[80:81]
	v_lshl_add_u64 v[80:81], v[80:81], 0, v[148:149]
	v_lshl_add_u64 v[82:83], v[80:81], 1, s[66:67]
	s_nop 1
	v_mov_b32_e32 v84, v188
	v_mov_b32_e32 v85, v189
	v_mov_b32_e32 v86, v190
	v_mov_b32_e32 v87, v191
	s_and_b64 vcc, exec, s[6:7]
	v_lshl_add_u64 v[80:81], v[80:81], 1, s[8:9]
	v_lshlrev_b32_e32 v88, 16, v84
	v_and_b32_e32 v89, 0xffff0000, v84
	v_lshlrev_b32_e32 v84, 16, v85
	v_and_b32_e32 v85, 0xffff0000, v85
	v_lshlrev_b32_e32 v90, 16, v86
	v_and_b32_e32 v91, 0xffff0000, v86
	v_lshlrev_b32_e32 v86, 16, v87
	v_and_b32_e32 v87, 0xffff0000, v87
	v_pk_add_f32 v[78:79], v[78:79], v[84:85]
	v_pk_add_f32 v[76:77], v[76:77], v[88:89]
	v_pk_add_f32 v[74:75], v[74:75], v[86:87]
	v_pk_add_f32 v[72:73], v[72:73], v[90:91]
	s_cbranch_vccnz .LBB0_1232
	v_cvt_pk_bf16_f32 v84, v76, v77
	v_cvt_pk_bf16_f32 v85, v78, v79
	v_cvt_pk_bf16_f32 v86, v72, v73
	v_cvt_pk_bf16_f32 v87, v74, v75
	global_store_dwordx4 v[80:81], v[84:87], off
.LBB0_1232:
	s_nop 1
	v_mov_b32_e32 v82, v192
	v_mov_b32_e32 v83, v193
	v_mov_b32_e32 v84, v194
	v_mov_b32_e32 v85, v195
	s_and_b64 vcc, exec, s[6:7]
	v_lshlrev_b32_e32 v86, 16, v82
	v_and_b32_e32 v87, 0xffff0000, v82
	v_lshlrev_b32_e32 v82, 16, v83
	v_and_b32_e32 v83, 0xffff0000, v83
	v_lshlrev_b32_e32 v88, 16, v84
	v_and_b32_e32 v89, 0xffff0000, v84
	v_lshlrev_b32_e32 v84, 16, v85
	v_and_b32_e32 v85, 0xffff0000, v85
	v_pk_add_f32 v[70:71], v[70:71], v[82:83]
	v_pk_add_f32 v[68:69], v[68:69], v[86:87]
	v_pk_add_f32 v[66:67], v[66:67], v[84:85]
	v_pk_add_f32 v[64:65], v[64:65], v[88:89]
	s_cbranch_vccnz .LBB0_1234
	v_cvt_pk_bf16_f32 v82, v68, v69
	v_cvt_pk_bf16_f32 v83, v70, v71
	v_cvt_pk_bf16_f32 v84, v64, v65
	v_cvt_pk_bf16_f32 v85, v66, v67
	global_store_dwordx4 v[80:81], v[82:85], off offset:256

; __device__ __forceinline__ unsigned pk2(float lo, float hi) { f32x2_t v = {lo, hi}; bf16x2_t b = __builtin_convertvector(v, bf16x2_t); return __builtin_bit_cast(unsigned, b); }
; __device__ __forceinline__ float bf_lo(unsigned w) { return __uint_as_float(w << 16); }
; __device__ __forceinline__ float bf_hi(unsigned w) { return __uint_as_float(w & 0xffff0000u); }
;     __device__ __forceinline__ void operator()(const f32x4 (&acc)[2][2][4][2], const Unit& u, int wr, int wc, int fr, int fq) const {
;     ...
;             for (int m = 0; m < 4; ++m) { const size_t off = (size_t)(row0 + ai * HALF + m * 16) * DM + col0; float sq = 0.f;
; #pragma unroll
;                 for (int bj = 0; bj < 2; ++bj) { f32x4 o[2];
;                     if (bbase) { const u32x4 w = *(const u32x4*)(bbase + off + bj * HALF);
;                         o[0] = (f32x4){bf_lo(w.x), bf_hi(w.x), bf_lo(w.y), bf_hi(w.y)} + acc[ai][bj][m][0]; o[1] = (f32x4){bf_lo(w.z), bf_hi(w.z), bf_lo(w.w), bf_hi(w.w)} + acc[ai][bj][m][1]; }
;                     else { o[0] = *(const f32x4*)(base + off + bj * HALF) + acc[ai][bj][m][0]; o[1] = *(const f32x4*)(base + off + bj * HALF + 4) + acc[ai][bj][m][1]; }
; #pragma unroll
;                     for (int n = 0; n < 2; ++n) { if (out) *(f32x4*)(out + off + bj * HALF + 4 * n) = o[n];
;                         sq += (o[n][0] * o[n][0] + o[n][1] * o[n][1]) + (o[n][2] * o[n][2] + o[n][3] * o[n][3]); }
;                     if (xb) { u32x4 w; w.x = pk2(o[0][0], o[0][1]); w.y = pk2(o[0][2], o[0][3]); w.z = pk2(o[1][0], o[1][1]); w.w = pk2(o[1][2], o[1][3]); *(u32x4*)(xb + off + bj * HALF) = w; if (xb2) *(u32x4*)(xb2 + off + bj * HALF) = w; } }
.LBB0_1238:
	v_lshl_add_u64 v[64:65], v[146:147], 0, s[22:23]
	v_lshl_add_u64 v[66:67], v[64:65], 1, s[66:67]
	s_waitcnt vmcnt(0)
	s_nop 1
	v_mov_b32_e32 v68, v196
	v_mov_b32_e32 v69, v197
	v_mov_b32_e32 v70, v198
	v_mov_b32_e32 v71, v199
	s_and_b64 vcc, exec, s[6:7]
	v_lshl_add_u64 v[64:65], v[64:65], 1, s[8:9]
	v_lshlrev_b32_e32 v72, 16, v68
	v_and_b32_e32 v73, 0xffff0000, v68
	v_lshlrev_b32_e32 v68, 16, v69
	v_and_b32_e32 v69, 0xffff0000, v69
	v_lshlrev_b32_e32 v74, 16, v70
	v_and_b32_e32 v75, 0xffff0000, v70
	v_lshlrev_b32_e32 v70, 16, v71
	v_and_b32_e32 v71, 0xffff0000, v71
	v_pk_add_f32 v[62:63], v[62:63], v[68:69]
	v_pk_add_f32 v[60:61], v[60:61], v[72:73]
	v_pk_add_f32 v[58:59], v[58:59], v[70:71]
	v_pk_add_f32 v[56:57], v[56:57], v[74:75]
	s_cbranch_vccnz .LBB0_1240
	v_cvt_pk_bf16_f32 v68, v60, v61
	v_cvt_pk_bf16_f32 v69, v62, v63
	v_cvt_pk_bf16_f32 v70, v56, v57
	v_cvt_pk_bf16_f32 v71, v58, v59
	global_store_dwordx4 v[64:65], v[68:71], off
.LBB0_1240:
	s_nop 1
	v_mov_b32_e32 v66, v200
	v_mov_b32_e32 v67, v201
	v_mov_b32_e32 v68, v202
	v_mov_b32_e32 v69, v203
	s_and_b64 vcc, exec, s[6:7]
	v_lshlrev_b32_e32 v70, 16, v66
	v_and_b32_e32 v71, 0xffff0000, v66
	v_lshlrev_b32_e32 v66, 16, v67
	v_and_b32_e32 v67, 0xffff0000, v67
	v_lshlrev_b32_e32 v72, 16, v68
	v_and_b32_e32 v73, 0xffff0000, v68
	v_lshlrev_b32_e32 v68, 16, v69
	v_and_b32_e32 v69, 0xffff0000, v69
	v_pk_add_f32 v[54:55], v[54:55], v[66:67]
	v_pk_add_f32 v[52:53], v[52:53], v[70:71]
	v_pk_add_f32 v[50:51], v[50:51], v[68:69]
	v_pk_add_f32 v[48:49], v[48:49], v[72:73]
	s_cbranch_vccnz .LBB0_1242
	v_cvt_pk_bf16_f32 v66, v52, v53
	v_cvt_pk_bf16_f32 v67, v54, v55
	v_cvt_pk_bf16_f32 v68, v48, v49
	v_cvt_pk_bf16_f32 v69, v50, v51
	global_store_dwordx4 v[64:65], v[66:69], off offset:256

; __device__ __forceinline__ unsigned pk2(float lo, float hi) { f32x2_t v = {lo, hi}; bf16x2_t b = __builtin_convertvector(v, bf16x2_t); return __builtin_bit_cast(unsigned, b); }
; __device__ __forceinline__ float bf_lo(unsigned w) { return __uint_as_float(w << 16); }
; __device__ __forceinline__ float bf_hi(unsigned w) { return __uint_as_float(w & 0xffff0000u); }
;     __device__ __forceinline__ void operator()(const f32x4 (&acc)[2][2][4][2], const Unit& u, int wr, int wc, int fr, int fq) const {
;     ...
;             for (int m = 0; m < 4; ++m) { const size_t off = (size_t)(row0 + ai * HALF + m * 16) * DM + col0; float sq = 0.f;
; #pragma unroll
;                 for (int bj = 0; bj < 2; ++bj) { f32x4 o[2];
;                     if (bbase) { const u32x4 w = *(const u32x4*)(bbase + off + bj * HALF);
;                         o[0] = (f32x4){bf_lo(w.x), bf_hi(w.x), bf_lo(w.y), bf_hi(w.y)} + acc[ai][bj][m][0]; o[1] = (f32x4){bf_lo(w.z), bf_hi(w.z), bf_lo(w.w), bf_hi(w.w)} + acc[ai][bj][m][1]; }
;                     else { o[0] = *(const f32x4*)(base + off + bj * HALF) + acc[ai][bj][m][0]; o[1] = *(const f32x4*)(base + off + bj * HALF + 4) + acc[ai][bj][m][1]; }
; #pragma unroll
;                     for (int n = 0; n < 2; ++n) { if (out) *(f32x4*)(out + off + bj * HALF + 4 * n) = o[n];
;                         sq += (o[n][0] * o[n][0] + o[n][1] * o[n][1]) + (o[n][2] * o[n][2] + o[n][3] * o[n][3]); }
;                     if (xb) { u32x4 w; w.x = pk2(o[0][0], o[0][1]); w.y = pk2(o[0][2], o[0][3]); w.z = pk2(o[1][0], o[1][1]); w.w = pk2(o[1][2], o[1][3]); *(u32x4*)(xb + off + bj * HALF) = w; if (xb2) *(u32x4*)(xb2 + off + bj * HALF) = w; } }
.LBB0_1246:
	v_lshl_add_u64 v[48:49], v[146:147], 0, s[24:25]
	v_lshl_add_u64 v[50:51], v[48:49], 1, s[66:67]
	s_nop 1
	v_mov_b32_e32 v52, v208
	v_mov_b32_e32 v53, v209
	v_mov_b32_e32 v54, v210
	v_mov_b32_e32 v55, v211
	s_and_b64 vcc, exec, s[6:7]
	v_lshl_add_u64 v[48:49], v[48:49], 1, s[8:9]
	v_lshlrev_b32_e32 v56, 16, v52
	v_and_b32_e32 v57, 0xffff0000, v52
	v_lshlrev_b32_e32 v52, 16, v53
	v_and_b32_e32 v53, 0xffff0000, v53
	v_lshlrev_b32_e32 v58, 16, v54
	v_and_b32_e32 v59, 0xffff0000, v54
	v_lshlrev_b32_e32 v54, 16, v55
	v_and_b32_e32 v55, 0xffff0000, v55
	v_pk_add_f32 v[46:47], v[46:47], v[52:53]
	v_pk_add_f32 v[44:45], v[44:45], v[56:57]
	v_pk_add_f32 v[42:43], v[42:43], v[54:55]
	v_pk_add_f32 v[40:41], v[40:41], v[58:59]
	s_cbranch_vccnz .LBB0_1248
	v_cvt_pk_bf16_f32 v52, v44, v45
	v_cvt_pk_bf16_f32 v53, v46, v47
	v_cvt_pk_bf16_f32 v54, v40, v41
	v_cvt_pk_bf16_f32 v55, v42, v43
	global_store_dwordx4 v[48:49], v[52:55], off
.LBB0_1248:
	s_nop 1
	v_mov_b32_e32 v50, v212
	v_mov_b32_e32 v51, v213
	v_mov_b32_e32 v52, v214
	v_mov_b32_e32 v53, v215
	s_and_b64 vcc, exec, s[6:7]
	v_lshlrev_b32_e32 v54, 16, v50
	v_and_b32_e32 v55, 0xffff0000, v50
	v_lshlrev_b32_e32 v50, 16, v51
	v_and_b32_e32 v51, 0xffff0000, v51
	v_lshlrev_b32_e32 v56, 16, v52
	v_and_b32_e32 v57, 0xffff0000, v52
	v_lshlrev_b32_e32 v52, 16, v53
	v_and_b32_e32 v53, 0xffff0000, v53
	v_pk_add_f32 v[38:39], v[38:39], v[50:51]
	v_pk_add_f32 v[36:37], v[36:37], v[54:55]
	v_pk_add_f32 v[34:35], v[34:35], v[52:53]
	v_pk_add_f32 v[32:33], v[32:33], v[56:57]
	s_cbranch_vccnz .LBB0_1250
	v_cvt_pk_bf16_f32 v50, v36, v37
	v_cvt_pk_bf16_f32 v51, v38, v39
	v_cvt_pk_bf16_f32 v52, v32, v33
	v_cvt_pk_bf16_f32 v53, v34, v35
	global_store_dwordx4 v[48:49], v[50:53], off offset:256

; __device__ __forceinline__ unsigned pk2(float lo, float hi) { f32x2_t v = {lo, hi}; bf16x2_t b = __builtin_convertvector(v, bf16x2_t); return __builtin_bit_cast(unsigned, b); }
; __device__ __forceinline__ float bf_lo(unsigned w) { return __uint_as_float(w << 16); }
; __device__ __forceinline__ float bf_hi(unsigned w) { return __uint_as_float(w & 0xffff0000u); }
;     __device__ __forceinline__ void operator()(const f32x4 (&acc)[2][2][4][2], const Unit& u, int wr, int wc, int fr, int fq) const {
;     ...
;             for (int m = 0; m < 4; ++m) { const size_t off = (size_t)(row0 + ai * HALF + m * 16) * DM + col0; float sq = 0.f;
; #pragma unroll
;                 for (int bj = 0; bj < 2; ++bj) { f32x4 o[2];
;                     if (bbase) { const u32x4 w = *(const u32x4*)(bbase + off + bj * HALF);
;                         o[0] = (f32x4){bf_lo(w.x), bf_hi(w.x), bf_lo(w.y), bf_hi(w.y)} + acc[ai][bj][m][0]; o[1] = (f32x4){bf_lo(w.z), bf_hi(w.z), bf_lo(w.w), bf_hi(w.w)} + acc[ai][bj][m][1]; }
;                     else { o[0] = *(const f32x4*)(base + off + bj * HALF) + acc[ai][bj][m][0]; o[1] = *(const f32x4*)(base + off + bj * HALF + 4) + acc[ai][bj][m][1]; }
; #pragma unroll
;                     for (int n = 0; n < 2; ++n) { if (out) *(f32x4*)(out + off + bj * HALF + 4 * n) = o[n];
;                         sq += (o[n][0] * o[n][0] + o[n][1] * o[n][1]) + (o[n][2] * o[n][2] + o[n][3] * o[n][3]); }
;                     if (xb) { u32x4 w; w.x = pk2(o[0][0], o[0][1]); w.y = pk2(o[0][2], o[0][3]); w.z = pk2(o[1][0], o[1][1]); w.w = pk2(o[1][2], o[1][3]); *(u32x4*)(xb + off + bj * HALF) = w; if (xb2) *(u32x4*)(xb2 + off + bj * HALF) = w; } }
.LBB0_1254:
	v_lshl_add_u64 v[32:33], v[146:147], 0, s[26:27]
	v_lshl_add_u64 v[34:35], v[32:33], 1, s[66:67]
	s_nop 1
	v_mov_b32_e32 v36, v164
	v_mov_b32_e32 v37, v165
	v_mov_b32_e32 v38, v166
	v_mov_b32_e32 v39, v167
	s_and_b64 vcc, exec, s[6:7]
	v_lshl_add_u64 v[32:33], v[32:33], 1, s[8:9]
	v_lshlrev_b32_e32 v40, 16, v36
	v_and_b32_e32 v41, 0xffff0000, v36
	v_lshlrev_b32_e32 v36, 16, v37
	v_and_b32_e32 v37, 0xffff0000, v37
	v_lshlrev_b32_e32 v42, 16, v38
	v_and_b32_e32 v43, 0xffff0000, v38
	v_lshlrev_b32_e32 v38, 16, v39
	v_and_b32_e32 v39, 0xffff0000, v39
	v_pk_add_f32 v[30:31], v[30:31], v[36:37]
	v_pk_add_f32 v[28:29], v[28:29], v[40:41]
	v_pk_add_f32 v[26:27], v[26:27], v[38:39]
	v_pk_add_f32 v[24:25], v[24:25], v[42:43]
	s_cbranch_vccnz .LBB0_1256
	v_cvt_pk_bf16_f32 v36, v28, v29
	v_cvt_pk_bf16_f32 v37, v30, v31
	v_cvt_pk_bf16_f32 v38, v24, v25
	v_cvt_pk_bf16_f32 v39, v26, v27
	global_store_dwordx4 v[32:33], v[36:39], off
.LBB0_1256:
	s_nop 1
	v_mov_b32_e32 v34, v168
	v_mov_b32_e32 v35, v169
	v_mov_b32_e32 v36, v170
	v_mov_b32_e32 v37, v171
	s_and_b64 vcc, exec, s[6:7]
	v_lshlrev_b32_e32 v38, 16, v34
	v_and_b32_e32 v39, 0xffff0000, v34
	v_lshlrev_b32_e32 v34, 16, v35
	v_and_b32_e32 v35, 0xffff0000, v35
	v_lshlrev_b32_e32 v40, 16, v36
	v_and_b32_e32 v41, 0xffff0000, v36
	v_lshlrev_b32_e32 v36, 16, v37
	v_and_b32_e32 v37, 0xffff0000, v37
	v_pk_add_f32 v[22:23], v[22:23], v[34:35]
	v_pk_add_f32 v[20:21], v[20:21], v[38:39]
	v_pk_add_f32 v[18:19], v[18:19], v[36:37]
	v_pk_add_f32 v[16:17], v[16:17], v[40:41]
	s_cbranch_vccnz .LBB0_1258
	v_cvt_pk_bf16_f32 v34, v20, v21
	v_cvt_pk_bf16_f32 v35, v22, v23
	v_cvt_pk_bf16_f32 v36, v16, v17
	v_cvt_pk_bf16_f32 v37, v18, v19
	global_store_dwordx4 v[32:33], v[34:37], off offset:256

; __device__ __forceinline__ unsigned pk2(float lo, float hi) { f32x2_t v = {lo, hi}; bf16x2_t b = __builtin_convertvector(v, bf16x2_t); return __builtin_bit_cast(unsigned, b); }
; __device__ __forceinline__ float bf_lo(unsigned w) { return __uint_as_float(w << 16); }
; __device__ __forceinline__ float bf_hi(unsigned w) { return __uint_as_float(w & 0xffff0000u); }
;     __device__ __forceinline__ void operator()(const f32x4 (&acc)[2][2][4][2], const Unit& u, int wr, int wc, int fr, int fq) const {
;     ...
;             for (int m = 0; m < 4; ++m) { const size_t off = (size_t)(row0 + ai * HALF + m * 16) * DM + col0; float sq = 0.f;
; #pragma unroll
;                 for (int bj = 0; bj < 2; ++bj) { f32x4 o[2];
;                     if (bbase) { const u32x4 w = *(const u32x4*)(bbase + off + bj * HALF);
;                         o[0] = (f32x4){bf_lo(w.x), bf_hi(w.x), bf_lo(w.y), bf_hi(w.y)} + acc[ai][bj][m][0]; o[1] = (f32x4){bf_lo(w.z), bf_hi(w.z), bf_lo(w.w), bf_hi(w.w)} + acc[ai][bj][m][1]; }
;                     else { o[0] = *(const f32x4*)(base + off + bj * HALF) + acc[ai][bj][m][0]; o[1] = *(const f32x4*)(base + off + bj * HALF + 4) + acc[ai][bj][m][1]; }
; #pragma unroll
;                     for (int n = 0; n < 2; ++n) { if (out) *(f32x4*)(out + off + bj * HALF + 4 * n) = o[n];
;                         sq += (o[n][0] * o[n][0] + o[n][1] * o[n][1]) + (o[n][2] * o[n][2] + o[n][3] * o[n][3]); }
;                     if (xb) { u32x4 w; w.x = pk2(o[0][0], o[0][1]); w.y = pk2(o[0][2], o[0][3]); w.z = pk2(o[1][0], o[1][1]); w.w = pk2(o[1][2], o[1][3]); *(u32x4*)(xb + off + bj * HALF) = w; if (xb2) *(u32x4*)(xb2 + off + bj * HALF) = w; } }
.LBB0_1262:
	v_lshl_add_u64 v[16:17], v[146:147], 0, s[28:29]
	v_lshl_add_u64 v[18:19], v[16:17], 1, s[66:67]
	s_nop 1
	v_mov_b32_e32 v20, v172
	v_mov_b32_e32 v21, v173
	v_mov_b32_e32 v22, v174
	v_mov_b32_e32 v23, v175
	s_and_b64 vcc, exec, s[6:7]
	v_lshl_add_u64 v[16:17], v[16:17], 1, s[8:9]
	v_lshlrev_b32_e32 v24, 16, v20
	v_and_b32_e32 v25, 0xffff0000, v20
	v_lshlrev_b32_e32 v20, 16, v21
	v_and_b32_e32 v21, 0xffff0000, v21
	v_lshlrev_b32_e32 v26, 16, v22
	v_and_b32_e32 v27, 0xffff0000, v22
	v_lshlrev_b32_e32 v22, 16, v23
	v_and_b32_e32 v23, 0xffff0000, v23
	v_pk_add_f32 v[14:15], v[14:15], v[20:21]
	v_pk_add_f32 v[12:13], v[12:13], v[24:25]
	v_pk_add_f32 v[10:11], v[10:11], v[22:23]
	v_pk_add_f32 v[8:9], v[8:9], v[26:27]
	s_cbranch_vccnz .LBB0_1264
	v_cvt_pk_bf16_f32 v20, v12, v13
	v_cvt_pk_bf16_f32 v21, v14, v15
	v_cvt_pk_bf16_f32 v22, v8, v9
	v_cvt_pk_bf16_f32 v23, v10, v11
	global_store_dwordx4 v[16:17], v[20:23], off
.LBB0_1264:
	s_nop 1
	v_mov_b32_e32 v18, v176
	v_mov_b32_e32 v19, v177
	v_mov_b32_e32 v20, v178
	v_mov_b32_e32 v21, v179
	s_and_b64 vcc, exec, s[6:7]
	v_lshlrev_b32_e32 v22, 16, v18
	v_and_b32_e32 v23, 0xffff0000, v18
	v_lshlrev_b32_e32 v18, 16, v19
	v_and_b32_e32 v19, 0xffff0000, v19
	v_lshlrev_b32_e32 v24, 16, v20
	v_and_b32_e32 v25, 0xffff0000, v20
	v_lshlrev_b32_e32 v20, 16, v21
	v_and_b32_e32 v21, 0xffff0000, v21
	v_pk_add_f32 v[6:7], v[6:7], v[18:19]
	v_pk_add_f32 v[4:5], v[4:5], v[22:23]
	v_pk_add_f32 v[2:3], v[2:3], v[20:21]
	v_pk_add_f32 v[0:1], v[0:1], v[24:25]
	s_cbranch_vccnz .LBB0_1266
	v_cvt_pk_bf16_f32 v18, v4, v5
	v_cvt_pk_bf16_f32 v19, v6, v7
	v_cvt_pk_bf16_f32 v20, v0, v1
	v_cvt_pk_bf16_f32 v21, v2, v3
	global_store_dwordx4 v[16:17], v[18:21], off offset:256

; __device__ __forceinline__ float bf_lo(unsigned w) { return __uint_as_float(w << 16); }
; __device__ __forceinline__ float bf_hi(unsigned w) { return __uint_as_float(w & 0xffff0000u); }
;     __device__ __forceinline__ void operator()(const f32x4 (&acc)[2][2][4][2], const Unit& u, int wr, int wc, int fr, int fq) const {
;     ...
;             for (int m = 0; m < 4; ++m) { const size_t off = (size_t)(row0 + ai * HALF + m * 16) * DM + col0; float sq = 0.f;
; #pragma unroll
;                 for (int bj = 0; bj < 2; ++bj) { f32x4 o[2];
;                     if (bbase) { const u32x4 w = *(const u32x4*)(bbase + off + bj * HALF);
;                         o[0] = (f32x4){bf_lo(w.x), bf_hi(w.x), bf_lo(w.y), bf_hi(w.y)} + acc[ai][bj][m][0]; o[1] = (f32x4){bf_lo(w.z), bf_hi(w.z), bf_lo(w.w), bf_hi(w.w)} + acc[ai][bj][m][1]; }
;                     else { o[0] = *(const f32x4*)(base + off + bj * HALF) + acc[ai][bj][m][0]; o[1] = *(const f32x4*)(base + off + bj * HALF + 4) + acc[ai][bj][m][1]; }
; #pragma unroll
;                     for (int n = 0; n < 2; ++n) { if (out) *(f32x4*)(out + off + bj * HALF + 4 * n) = o[n];
.LBB0_1410:
	s_andn2_b64 vcc, exec, s[12:13]
	s_cbranch_vccnz .LBB0_1412
	v_lshl_add_u32 v148, s49, 8, v150
	v_lshl_or_b32 v146, s48, 8, v152
	v_ashrrev_i32_e32 v149, 31, v148
	v_ashrrev_i32_e32 v147, 31, v146
	v_lshlrev_b64 v[144:145], 10, v[148:149]
	v_lshl_add_u64 v[144:145], v[144:145], 0, v[146:147]
	v_lshl_add_u64 v[160:161], v[144:145], 1, s[8:9]
	v_mov_b32_e32 v248, v160
	v_mov_b32_e32 v249, v161
	global_load_dwordx4 v[168:171], v[248:249], off
	global_load_dwordx4 v[172:175], v[248:249], off offset:256
	s_mov_b32 s98, 0x8000
	s_mov_b32 s99, 0
	v_lshl_add_u64 v[250:251], v[248:249], 0, s[98:99]
	global_load_dwordx4 v[176:179], v[250:251], off
	global_load_dwordx4 v[180:183], v[250:251], off offset:256
	s_mov_b32 s98, 0x10000
	s_mov_b32 s99, 0
	v_lshl_add_u64 v[250:251], v[248:249], 0, s[98:99]
	global_load_dwordx4 v[184:187], v[250:251], off
	global_load_dwordx4 v[188:191], v[250:251], off offset:256
	s_mov_b32 s98, 0x18000
	s_mov_b32 s99, 0
	v_lshl_add_u64 v[250:251], v[248:249], 0, s[98:99]
	global_load_dwordx4 v[192:195], v[250:251], off
	global_load_dwordx4 v[196:199], v[250:251], off offset:256
	s_waitcnt vmcnt(0)
	s_nop 1
	v_mov_b32_e32 v156, v168
	v_mov_b32_e32 v157, v169
	v_mov_b32_e32 v158, v170
	v_mov_b32_e32 v159, v171
	v_lshl_add_u64 v[162:163], v[144:145], 2, s[66:67]
	v_lshlrev_b32_e32 v166, 16, v156
	v_and_b32_e32 v167, 0xffff0000, v156
	v_lshlrev_b32_e32 v156, 16, v157
	v_and_b32_e32 v157, 0xffff0000, v157
	v_lshlrev_b32_e32 v164, 16, v158
	v_and_b32_e32 v165, 0xffff0000, v158
	v_lshlrev_b32_e32 v158, 16, v159
	v_and_b32_e32 v159, 0xffff0000, v159
	v_pk_add_f32 v[126:127], v[126:127], v[156:157]
	v_pk_add_f32 v[124:125], v[124:125], v[166:167]
	v_pk_add_f32 v[122:123], v[122:123], v[158:159]
	v_pk_add_f32 v[120:121], v[120:121], v[164:165]
	global_store_dwordx4 v[162:163], v[124:127], off
	global_store_dwordx4 v[162:163], v[120:123], off offset:16
	s_nop 1
	v_mov_b32_e32 v120, v172
	v_mov_b32_e32 v121, v173
	v_mov_b32_e32 v122, v174
	v_mov_b32_e32 v123, v175
	v_or_b32_e32 v124, 16, v148
	v_ashrrev_i32_e32 v125, 31, v124
	v_lshlrev_b64 v[124:125], 10, v[124:125]
	v_lshl_add_u64 v[124:125], v[124:125], 0, v[146:147]
	v_lshl_add_u64 v[126:127], v[124:125], 1, s[8:9]
	v_lshlrev_b32_e32 v158, 16, v120
	v_and_b32_e32 v159, 0xffff0000, v120
	v_lshlrev_b32_e32 v120, 16, v121
	v_and_b32_e32 v121, 0xffff0000, v121
	v_lshlrev_b32_e32 v156, 16, v122
	v_and_b32_e32 v157, 0xffff0000, v122
	v_lshlrev_b32_e32 v122, 16, v123
	v_and_b32_e32 v123, 0xffff0000, v123
	v_pk_add_f32 v[118:119], v[118:119], v[120:121]
	v_pk_add_f32 v[116:117], v[116:117], v[158:159]
	v_pk_add_f32 v[114:115], v[114:115], v[122:123]
	v_pk_add_f32 v[112:113], v[112:113], v[156:157]
	global_store_dwordx4 v[162:163], v[116:119], off offset:512
	global_store_dwordx4 v[162:163], v[112:115], off offset:528
	s_nop 1
	v_mov_b32_e32 v112, v176
	v_mov_b32_e32 v113, v177
	v_mov_b32_e32 v114, v178
	v_mov_b32_e32 v115, v179
	v_lshl_add_u64 v[116:117], v[124:125], 2, s[66:67]
	v_lshlrev_b32_e32 v120, 16, v112
	v_and_b32_e32 v121, 0xffff0000, v112
	v_lshlrev_b32_e32 v112, 16, v113
	v_and_b32_e32 v113, 0xffff0000, v113
	v_lshlrev_b32_e32 v118, 16, v114
	v_and_b32_e32 v119, 0xffff0000, v114
	v_lshlrev_b32_e32 v114, 16, v115
	v_and_b32_e32 v115, 0xffff0000, v115
	v_pk_add_f32 v[110:111], v[110:111], v[112:113]
	v_pk_add_f32 v[108:109], v[108:109], v[120:121]
	v_pk_add_f32 v[106:107], v[106:107], v[114:115]
	v_pk_add_f32 v[104:105], v[104:105], v[118:119]
	global_store_dwordx4 v[116:117], v[108:111], off
	global_store_dwordx4 v[116:117], v[104:107], off offset:16
	s_nop 1
	v_mov_b32_e32 v104, v180
	v_mov_b32_e32 v105, v181
	v_mov_b32_e32 v106, v182
	v_mov_b32_e32 v107, v183
	s_mov_b32 s98, 0x40000
	s_mov_b32 s99, 0
	v_lshl_add_u64 v[250:251], v[248:249], 0, s[98:99]
	global_load_dwordx4 v[200:203], v[250:251], off
	global_load_dwordx4 v[204:207], v[250:251], off offset:256
	s_mov_b32 s98, 0x48000
	s_mov_b32 s99, 0
	v_lshl_add_u64 v[250:251], v[248:249], 0, s[98:99]
	global_load_dwordx4 v[208:211], v[250:251], off
	global_load_dwordx4 v[212:215], v[250:251], off offset:256
	s_mov_b32 s98, 0x50000
	s_mov_b32 s99, 0
	v_lshl_add_u64 v[250:251], v[248:249], 0, s[98:99]
	global_load_dwordx4 v[168:171], v[250:251], off
	global_load_dwordx4 v[172:175], v[250:251], off offset:256
	s_mov_b32 s98, 0x58000
	s_mov_b32 s99, 0
	v_lshl_add_u64 v[250:251], v[248:249], 0, s[98:99]
	global_load_dwordx4 v[176:179], v[250:251], off
	global_load_dwordx4 v[180:183], v[250:251], off offset:256
	v_or_b32_e32 v108, 32, v148
	v_ashrrev_i32_e32 v109, 31, v108
	v_lshlrev_b64 v[108:109], 10, v[108:109]
	v_lshl_add_u64 v[108:109], v[108:109], 0, v[146:147]
	v_lshl_add_u64 v[110:111], v[108:109], 1, s[8:9]
	v_lshlrev_b32_e32 v114, 16, v104
	v_and_b32_e32 v115, 0xffff0000, v104
	v_lshlrev_b32_e32 v104, 16, v105
	v_and_b32_e32 v105, 0xffff0000, v105
	v_lshlrev_b32_e32 v112, 16, v106
	v_and_b32_e32 v113, 0xffff0000, v106
	v_lshlrev_b32_e32 v106, 16, v107
	v_and_b32_e32 v107, 0xffff0000, v107
	v_pk_add_f32 v[102:103], v[102:103], v[104:105]
	v_pk_add_f32 v[100:101], v[100:101], v[114:115]
	v_pk_add_f32 v[98:99], v[98:99], v[106:107]
	v_pk_add_f32 v[96:97], v[96:97], v[112:113]
	global_store_dwordx4 v[116:117], v[100:103], off offset:512
	global_store_dwordx4 v[116:117], v[96:99], off offset:528
	s_nop 1
	v_mov_b32_e32 v96, v184
	v_mov_b32_e32 v97, v185
	v_mov_b32_e32 v98, v186
	v_mov_b32_e32 v99, v187
	v_lshl_add_u64 v[100:101], v[108:109], 2, s[66:67]
	v_lshlrev_b32_e32 v104, 16, v96
	v_and_b32_e32 v105, 0xffff0000, v96
	v_lshlrev_b32_e32 v96, 16, v97
	v_and_b32_e32 v97, 0xffff0000, v97
	v_lshlrev_b32_e32 v102, 16, v98
; __device__ __forceinline__ float bf_lo(unsigned w) { return __uint_as_float(w << 16); }
; __device__ __forceinline__ float bf_hi(unsigned w) { return __uint_as_float(w & 0xffff0000u); }
;     __device__ __forceinline__ void operator()(const f32x4 (&acc)[2][2][4][2], const Unit& u, int wr, int wc, int fr, int fq) const {
;     ...
;             for (int m = 0; m < 4; ++m) { const size_t off = (size_t)(row0 + ai * HALF + m * 16) * DM + col0; float sq = 0.f;
; #pragma unroll
;                 for (int bj = 0; bj < 2; ++bj) { f32x4 o[2];
;                     if (bbase) { const u32x4 w = *(const u32x4*)(bbase + off + bj * HALF);
;                         o[0] = (f32x4){bf_lo(w.x), bf_hi(w.x), bf_lo(w.y), bf_hi(w.y)} + acc[ai][bj][m][0]; o[1] = (f32x4){bf_lo(w.z), bf_hi(w.z), bf_lo(w.w), bf_hi(w.w)} + acc[ai][bj][m][1]; }
;                     else { o[0] = *(const f32x4*)(base + off + bj * HALF) + acc[ai][bj][m][0]; o[1] = *(const f32x4*)(base + off + bj * HALF + 4) + acc[ai][bj][m][1]; }
; #pragma unroll
;                     for (int n = 0; n < 2; ++n) { if (out) *(f32x4*)(out + off + bj * HALF + 4 * n) = o[n];
	v_and_b32_e32 v103, 0xffff0000, v98
	v_lshlrev_b32_e32 v98, 16, v99
	v_and_b32_e32 v99, 0xffff0000, v99
	v_pk_add_f32 v[94:95], v[94:95], v[96:97]
	v_pk_add_f32 v[92:93], v[92:93], v[104:105]
	v_pk_add_f32 v[90:91], v[90:91], v[98:99]
	v_pk_add_f32 v[88:89], v[88:89], v[102:103]
	global_store_dwordx4 v[100:101], v[92:95], off
	global_store_dwordx4 v[100:101], v[88:91], off offset:16
	s_nop 1
	v_mov_b32_e32 v88, v188
	v_mov_b32_e32 v89, v189
	v_mov_b32_e32 v90, v190
	v_mov_b32_e32 v91, v191
	v_or_b32_e32 v92, 48, v148
	v_ashrrev_i32_e32 v93, 31, v92
	v_lshlrev_b64 v[92:93], 10, v[92:93]
	v_lshl_add_u64 v[92:93], v[92:93], 0, v[146:147]
	v_lshl_add_u64 v[94:95], v[92:93], 1, s[8:9]
	v_lshlrev_b32_e32 v98, 16, v88
	v_and_b32_e32 v99, 0xffff0000, v88
	v_lshlrev_b32_e32 v88, 16, v89
	v_and_b32_e32 v89, 0xffff0000, v89
	v_lshlrev_b32_e32 v96, 16, v90
	v_and_b32_e32 v97, 0xffff0000, v90
	v_lshlrev_b32_e32 v90, 16, v91
	v_and_b32_e32 v91, 0xffff0000, v91
	v_pk_add_f32 v[86:87], v[86:87], v[88:89]
	v_pk_add_f32 v[84:85], v[84:85], v[98:99]
	v_pk_add_f32 v[82:83], v[82:83], v[90:91]
	v_pk_add_f32 v[80:81], v[80:81], v[96:97]
	global_store_dwordx4 v[100:101], v[84:87], off offset:512
	global_store_dwordx4 v[100:101], v[80:83], off offset:528
	s_nop 1
	v_mov_b32_e32 v80, v192
	v_mov_b32_e32 v81, v193
	v_mov_b32_e32 v82, v194
	v_mov_b32_e32 v83, v195
	v_lshl_add_u64 v[84:85], v[92:93], 2, s[66:67]
	v_lshlrev_b32_e32 v88, 16, v80
	v_and_b32_e32 v89, 0xffff0000, v80
	v_lshlrev_b32_e32 v80, 16, v81
	v_and_b32_e32 v81, 0xffff0000, v81
	v_lshlrev_b32_e32 v86, 16, v82
	v_and_b32_e32 v87, 0xffff0000, v82
	v_lshlrev_b32_e32 v82, 16, v83
	v_and_b32_e32 v83, 0xffff0000, v83
	v_pk_add_f32 v[78:79], v[78:79], v[80:81]
	v_pk_add_f32 v[76:77], v[76:77], v[88:89]
	v_pk_add_f32 v[74:75], v[74:75], v[82:83]
	v_pk_add_f32 v[72:73], v[72:73], v[86:87]
	global_store_dwordx4 v[84:85], v[76:79], off
	global_store_dwordx4 v[84:85], v[72:75], off offset:16
	s_nop 1
	v_mov_b32_e32 v72, v196
	v_mov_b32_e32 v73, v197
	v_mov_b32_e32 v74, v198
	v_mov_b32_e32 v75, v199
	v_lshl_add_u64 v[76:77], v[144:145], 0, s[14:15]
	v_lshl_add_u64 v[78:79], v[76:77], 1, s[8:9]
	v_lshlrev_b32_e32 v82, 16, v72
	v_and_b32_e32 v83, 0xffff0000, v72
	v_lshlrev_b32_e32 v72, 16, v73
	v_and_b32_e32 v73, 0xffff0000, v73
	v_lshlrev_b32_e32 v80, 16, v74
	v_and_b32_e32 v81, 0xffff0000, v74
	v_lshlrev_b32_e32 v74, 16, v75
	v_and_b32_e32 v75, 0xffff0000, v75
	v_pk_add_f32 v[70:71], v[70:71], v[72:73]
	v_pk_add_f32 v[68:69], v[68:69], v[82:83]
	v_pk_add_f32 v[66:67], v[66:67], v[74:75]
	v_pk_add_f32 v[64:65], v[64:65], v[80:81]
	global_store_dwordx4 v[84:85], v[68:71], off offset:512
	global_store_dwordx4 v[84:85], v[64:67], off offset:528
	s_waitcnt vmcnt(0)
; __device__ __forceinline__ float bf_lo(unsigned w) { return __uint_as_float(w << 16); }
; __device__ __forceinline__ float bf_hi(unsigned w) { return __uint_as_float(w & 0xffff0000u); }
;     __device__ __forceinline__ void operator()(const f32x4 (&acc)[2][2][4][2], const Unit& u, int wr, int wc, int fr, int fq) const {
;     ...
;             for (int m = 0; m < 4; ++m) { const size_t off = (size_t)(row0 + ai * HALF + m * 16) * DM + col0; float sq = 0.f;
; #pragma unroll
;                 for (int bj = 0; bj < 2; ++bj) { f32x4 o[2];
;                     if (bbase) { const u32x4 w = *(const u32x4*)(bbase + off + bj * HALF);
;                         o[0] = (f32x4){bf_lo(w.x), bf_hi(w.x), bf_lo(w.y), bf_hi(w.y)} + acc[ai][bj][m][0]; o[1] = (f32x4){bf_lo(w.z), bf_hi(w.z), bf_lo(w.w), bf_hi(w.w)} + acc[ai][bj][m][1]; }
;                     else { o[0] = *(const f32x4*)(base + off + bj * HALF) + acc[ai][bj][m][0]; o[1] = *(const f32x4*)(base + off + bj * HALF + 4) + acc[ai][bj][m][1]; }
; #pragma unroll
;                     for (int n = 0; n < 2; ++n) { if (out) *(f32x4*)(out + off + bj * HALF + 4 * n) = o[n];
	s_nop 1
	v_mov_b32_e32 v64, v200
	v_mov_b32_e32 v65, v201
	v_mov_b32_e32 v66, v202
	v_mov_b32_e32 v67, v203
	v_lshl_add_u64 v[68:69], v[76:77], 2, s[66:67]
	v_lshlrev_b32_e32 v72, 16, v64
	v_and_b32_e32 v73, 0xffff0000, v64
	v_lshlrev_b32_e32 v64, 16, v65
	v_and_b32_e32 v65, 0xffff0000, v65
	v_lshlrev_b32_e32 v70, 16, v66
	v_and_b32_e32 v71, 0xffff0000, v66
	v_lshlrev_b32_e32 v66, 16, v67
	v_and_b32_e32 v67, 0xffff0000, v67
	v_pk_add_f32 v[62:63], v[62:63], v[64:65]
	v_pk_add_f32 v[60:61], v[60:61], v[72:73]
	v_pk_add_f32 v[58:59], v[58:59], v[66:67]
	v_pk_add_f32 v[56:57], v[56:57], v[70:71]
	global_store_dwordx4 v[68:69], v[60:63], off
	global_store_dwordx4 v[68:69], v[56:59], off offset:16
	s_nop 1
	v_mov_b32_e32 v56, v204
	v_mov_b32_e32 v57, v205
	v_mov_b32_e32 v58, v206
	v_mov_b32_e32 v59, v207
	v_lshl_add_u64 v[60:61], v[144:145], 0, s[16:17]
	v_lshl_add_u64 v[62:63], v[60:61], 1, s[8:9]
	v_lshlrev_b32_e32 v66, 16, v56
	v_and_b32_e32 v67, 0xffff0000, v56
	v_lshlrev_b32_e32 v56, 16, v57
	v_and_b32_e32 v57, 0xffff0000, v57
	v_lshlrev_b32_e32 v64, 16, v58
	v_and_b32_e32 v65, 0xffff0000, v58
	v_lshlrev_b32_e32 v58, 16, v59
	v_and_b32_e32 v59, 0xffff0000, v59
	v_pk_add_f32 v[54:55], v[54:55], v[56:57]
	v_pk_add_f32 v[52:53], v[52:53], v[66:67]
	v_pk_add_f32 v[50:51], v[50:51], v[58:59]
	v_pk_add_f32 v[48:49], v[48:49], v[64:65]
	global_store_dwordx4 v[68:69], v[52:55], off offset:512
	global_store_dwordx4 v[68:69], v[48:51], off offset:528
	s_nop 1
	v_mov_b32_e32 v48, v208
	v_mov_b32_e32 v49, v209
	v_mov_b32_e32 v50, v210
	v_mov_b32_e32 v51, v211
	v_lshl_add_u64 v[52:53], v[60:61], 2, s[66:67]
	v_lshlrev_b32_e32 v56, 16, v48
	v_and_b32_e32 v57, 0xffff0000, v48
	v_lshlrev_b32_e32 v48, 16, v49
	v_and_b32_e32 v49, 0xffff0000, v49
	v_lshlrev_b32_e32 v54, 16, v50
	v_and_b32_e32 v55, 0xffff0000, v50
	v_lshlrev_b32_e32 v50, 16, v51
	v_and_b32_e32 v51, 0xffff0000, v51
	v_pk_add_f32 v[46:47], v[46:47], v[48:49]
	v_pk_add_f32 v[44:45], v[44:45], v[56:57]
	v_pk_add_f32 v[42:43], v[42:43], v[50:51]
	v_pk_add_f32 v[40:41], v[40:41], v[54:55]
	global_store_dwordx4 v[52:53], v[44:47], off
	global_store_dwordx4 v[52:53], v[40:43], off offset:16
	s_nop 1
	v_mov_b32_e32 v40, v212
	v_mov_b32_e32 v41, v213
	v_mov_b32_e32 v42, v214
	v_mov_b32_e32 v43, v215
	v_lshl_add_u64 v[44:45], v[144:145], 0, s[18:19]
	v_lshl_add_u64 v[46:47], v[44:45], 1, s[8:9]
	v_lshlrev_b32_e32 v50, 16, v40
	v_and_b32_e32 v51, 0xffff0000, v40
	v_lshlrev_b32_e32 v40, 16, v41
	v_and_b32_e32 v41, 0xffff0000, v41
	v_lshlrev_b32_e32 v48, 16, v42
	v_and_b32_e32 v49, 0xffff0000, v42
	v_lshlrev_b32_e32 v42, 16, v43
	v_and_b32_e32 v43, 0xffff0000, v43
	v_pk_add_f32 v[38:39], v[38:39], v[40:41]
	v_pk_add_f32 v[36:37], v[36:37], v[50:51]
	v_pk_add_f32 v[34:35], v[34:35], v[42:43]
	v_pk_add_f32 v[32:33], v[32:33], v[48:49]
	global_store_dwordx4 v[52:53], v[36:39], off offset:512
	global_store_dwordx4 v[52:53], v[32:35], off offset:528
	s_nop 1
	v_mov_b32_e32 v32, v168
	v_mov_b32_e32 v33, v169
	v_mov_b32_e32 v34, v170
	v_mov_b32_e32 v35, v171
	v_lshl_add_u64 v[36:37], v[44:45], 2, s[66:67]
	v_lshlrev_b32_e32 v40, 16, v32
	v_and_b32_e32 v41, 0xffff0000, v32
	v_lshlrev_b32_e32 v32, 16, v33
	v_and_b32_e32 v33, 0xffff0000, v33
	v_lshlrev_b32_e32 v38, 16, v34
	v_and_b32_e32 v39, 0xffff0000, v34
	v_lshlrev_b32_e32 v34, 16, v35
	v_and_b32_e32 v35, 0xffff0000, v35
	v_pk_add_f32 v[30:31], v[30:31], v[32:33]
	v_pk_add_f32 v[28:29], v[28:29], v[40:41]
	v_pk_add_f32 v[26:27], v[26:27], v[34:35]
	v_pk_add_f32 v[24:25], v[24:25], v[38:39]
	global_store_dwordx4 v[36:37], v[28:31], off
	global_store_dwordx4 v[36:37], v[24:27], off offset:16
	s_nop 1
	v_mov_b32_e32 v24, v172
	v_mov_b32_e32 v25, v173
	v_mov_b32_e32 v26, v174
	v_mov_b32_e32 v27, v175
	v_lshl_add_u64 v[28:29], v[144:145], 0, s[20:21]
	v_lshl_add_u64 v[30:31], v[28:29], 1, s[8:9]
	v_lshlrev_b32_e32 v34, 16, v24
	v_and_b32_e32 v35, 0xffff0000, v24
	v_lshlrev_b32_e32 v24, 16, v25
	v_and_b32_e32 v25, 0xffff0000, v25
	v_lshlrev_b32_e32 v32, 16, v26
	v_and_b32_e32 v33, 0xffff0000, v26
	v_lshlrev_b32_e32 v26, 16, v27
	v_and_b32_e32 v27, 0xffff0000, v27
	v_pk_add_f32 v[22:23], v[22:23], v[24:25]
	v_pk_add_f32 v[20:21], v[20:21], v[34:35]
	v_pk_add_f32 v[18:19], v[18:19], v[26:27]
	v_pk_add_f32 v[16:17], v[16:17], v[32:33]
	global_store_dwordx4 v[36:37], v[20:23], off offset:512
	global_store_dwordx4 v[36:37], v[16:19], off offset:528
	s_nop 1
	v_mov_b32_e32 v16, v176
	v_mov_b32_e32 v17, v177
	v_mov_b32_e32 v18, v178
	v_mov_b32_e32 v19, v179
	v_lshl_add_u64 v[20:21], v[28:29], 2, s[66:67]
	v_lshlrev_b32_e32 v24, 16, v16
	v_and_b32_e32 v25, 0xffff0000, v16
	v_lshlrev_b32_e32 v16, 16, v17
	v_and_b32_e32 v17, 0xffff0000, v17
	v_lshlrev_b32_e32 v22, 16, v18
	v_and_b32_e32 v23, 0xffff0000, v18
	v_lshlrev_b32_e32 v18, 16, v19
	v_and_b32_e32 v19, 0xffff0000, v19
	v_pk_add_f32 v[14:15], v[14:15], v[16:17]
	v_pk_add_f32 v[12:13], v[12:13], v[24:25]
	v_pk_add_f32 v[10:11], v[10:11], v[18:19]
	v_pk_add_f32 v[8:9], v[8:9], v[22:23]
	global_store_dwordx4 v[20:21], v[12:15], off
	global_store_dwordx4 v[20:21], v[8:11], off offset:16
	s_nop 1
	v_mov_b32_e32 v8, v180
	v_mov_b32_e32 v9, v181
	v_mov_b32_e32 v10, v182
	v_mov_b32_e32 v11, v183
	v_lshlrev_b32_e32 v14, 16, v8
	v_and_b32_e32 v15, 0xffff0000, v8
	v_lshlrev_b32_e32 v8, 16, v9
	v_and_b32_e32 v9, 0xffff0000, v9
	v_lshlrev_b32_e32 v12, 16, v10
	v_and_b32_e32 v13, 0xffff0000, v10
	v_lshlrev_b32_e32 v10, 16, v11
	v_and_b32_e32 v11, 0xffff0000, v11
	v_pk_add_f32 v[6:7], v[6:7], v[8:9]
	v_pk_add_f32 v[4:5], v[4:5], v[14:15]
	v_pk_add_f32 v[2:3], v[2:3], v[10:11]
	v_pk_add_f32 v[0:1], v[0:1], v[12:13]
	global_store_dwordx4 v[20:21], v[4:7], off offset:512
	global_store_dwordx4 v[20:21], v[0:3], off offset:528
